# E28: residual-add GEMM epilogues (Wo, MLP-down) issue each accumulator row's 4 gate + 4 residual loads together with counted waits, on top of E26
# speedup vs baseline: 1.0313x; 1.0105x over previous
; #define PG8_STAGE(bufoff, gbase, voff) do { _Pragma("unroll") for (int _i = 0; _i < 2; ++_i) \
;     __builtin_amdgcn_global_load_lds((const unsigned*)((const char*)(gbase) + (voff)[_i]), (LAS unsigned*)(lds + (bufoff) + ldsw + _i * 8192), 16, 0, 0); } while (0)
; #define PG8_LDA(dst, b, h) do { _Pragma("unroll") for (int m = 0; m < 4; ++m) _Pragma("unroll") for (int k = 0; k < 2; ++k) dst[m][k] = *(const LAS bf16x8*)(lds + PG8_SA(b, h) + aoff + m * 2048 + k * 1024); } while (0)
; #define PG8_LDB(dst, b, h) do { _Pragma("unroll") for (int n = 0; n < 2; ++n) _Pragma("unroll") for (int k = 0; k < 2; ++k) dst[n][k] = *(const LAS bf16x8*)(lds + PG8_SB(b, h) + boff + n * 2048 + k * 1024); } while (0)
; #define PG8_BAR __builtin_amdgcn_s_barrier()
; template <class Epi, class Sched>
; __device__ __forceinline__ void gemm_phase(LAS unsigned char* lds, const Gemm g, const Sched& S, const Epi& E) {
;     ...
;     for (int t = 0; t < nt; t += 2) {
;       const bool last = (t == nt - 2);
;       const char* a1 = cA + (size_t)(t + 1) * kstep;
;       const char* a2 = last ? nA : cA + (size_t)(t + 2) * kstep; const char* b2 = last ? nB : cB + (size_t)(t + 2) * kstep;
;       const char* a3 = a2 + kstep; const char* b3 = b2 + kstep;
;       PG8_LDB(B0, 0, 0); PG8_SCHED; PG8_LDA(At, 0, 0); PG8_STAGE(PG8_SA(1, 1), a1 + hstepA, voffA);
;       PG8_WAIT_L(8); PG8_BAR; PG8_WAIT_L(0); PG8_MMA(0, 0, At, B0); PG8_BAR; PG8_SCHED;
;       PG8_LDB(B1, 0, 1); PG8_STAGE(PG8_SB(0, 0), b2, voffB);
;       PG8_BAR; PG8_WAIT_L(0); PG8_MMA(0, 1, At, B1); PG8_BAR;
;       PG8_LDA(At, 0, 1); PG8_STAGE(PG8_SA(0, 0), a2, voffA);
;       PG8_BAR; PG8_WAIT_L(0); PG8_MMA(1, 0, At, B0); PG8_BAR; PG8_SCHED;
;       PG8_STAGE(PG8_SB(0, 1), b2 + hstepB, voffB);
;       PG8_WAIT_V(6); PG8_BAR; PG8_MMA(1, 1, At, B1); PG8_BAR;
;       PG8_LDB(B0, 1, 0); PG8_SCHED; PG8_LDA(At, 1, 0); PG8_STAGE(PG8_SA(0, 1), a2 + hstepA, voffA);
;       PG8_WAIT_L(8); PG8_BAR; PG8_WAIT_L(0); PG8_MMA(0, 0, At, B0); PG8_BAR; PG8_SCHED;
;       PG8_LDB(B1, 1, 1); PG8_STAGE(PG8_SB(1, 0), b3, voffB);
;       PG8_BAR; PG8_WAIT_L(0); PG8_MMA(0, 1, At, B1); PG8_BAR;
;       PG8_LDA(At, 1, 1); PG8_STAGE(PG8_SA(1, 0), a3, voffA);
;       PG8_BAR; PG8_WAIT_L(0); PG8_MMA(1, 0, At, B0); PG8_BAR; PG8_SCHED;
;       PG8_STAGE(PG8_SB(1, 1), b3 + hstepB, voffB);
;       PG8_WAIT_V(6); PG8_BAR; PG8_MMA(1, 1, At, B1); PG8_BAR;
.LBB0_2633:
	s_add_u32 s36, s28, 0xfffc0080
	s_addc_u32 s37, s29, -1
	s_add_i32 s76, 16, 0x10000
	v_add_u32_e32 v149, s76, v146
	ds_read_b128 v[136:139], v149
	ds_read_b128 v[140:143], v149 offset:1024
	ds_read_b128 v[150:153], v149 offset:2048
	ds_read_b128 v[154:157], v149 offset:3072
	s_cmp_eq_u32 s86, 12
	s_cselect_b32 s39, s21, s37
	s_cselect_b32 s38, s82, s36
	s_cselect_b32 s37, s19, s85
	s_cselect_b32 s36, s83, s84
	v_lshl_add_u64 v[214:215], s[28:29], 0, v[132:133]
	s_add_i32 m0, s48, 0xc000
	ds_read_b128 v[158:161], v148
	ds_read_b128 v[162:165], v148 offset:1024
	ds_read_b128 v[166:169], v148 offset:2048
	ds_read_b128 v[170:173], v148 offset:3072
	ds_read_b128 v[174:177], v148 offset:4096
	ds_read_b128 v[178:181], v148 offset:5120
	ds_read_b128 v[182:185], v148 offset:6144
	ds_read_b128 v[198:201], v148 offset:7168
	global_load_lds_dwordx4 v[214:215], off
	v_lshl_add_u64 v[214:215], s[28:29], 0, v[134:135]
	s_add_i32 m0, s48, 0xe000
	s_nop 0
	global_load_lds_dwordx4 v[214:215], off
	s_waitcnt lgkmcnt(8)
	s_barrier
	s_waitcnt lgkmcnt(0)
	s_setprio 1
	s_waitcnt lgkmcnt(0)
	v_mfma_f32_16x16x32_bf16 v[124:127], v[136:139], v[158:161], v[124:127]
	v_mfma_f32_16x16x32_bf16 v[120:123], v[150:153], v[158:161], v[120:123]
	v_mfma_f32_16x16x32_bf16 v[112:115], v[136:139], v[166:169], v[112:115]
	v_mfma_f32_16x16x32_bf16 v[104:107], v[150:153], v[166:169], v[104:107]
	v_mfma_f32_16x16x32_bf16 v[96:99], v[136:139], v[174:177], v[96:99]
	v_mfma_f32_16x16x32_bf16 v[88:91], v[150:153], v[174:177], v[88:91]
	v_mfma_f32_16x16x32_bf16 v[80:83], v[136:139], v[182:185], v[80:83]
	v_mfma_f32_16x16x32_bf16 v[72:75], v[150:153], v[182:185], v[72:75]
	v_mfma_f32_16x16x32_bf16 v[124:127], v[140:143], v[162:165], v[124:127]
	v_mfma_f32_16x16x32_bf16 v[120:123], v[154:157], v[162:165], v[120:123]
	v_mfma_f32_16x16x32_bf16 v[112:115], v[140:143], v[170:173], v[112:115]
	v_mfma_f32_16x16x32_bf16 v[104:107], v[154:157], v[170:173], v[104:107]
	v_mfma_f32_16x16x32_bf16 v[96:99], v[140:143], v[178:181], v[96:99]
	v_mfma_f32_16x16x32_bf16 v[88:91], v[154:157], v[178:181], v[88:91]
	v_mfma_f32_16x16x32_bf16 v[80:83], v[140:143], v[198:201], v[80:83]
	v_mfma_f32_16x16x32_bf16 v[72:75], v[154:157], v[198:201], v[72:75]
	s_setprio 0
	s_barrier
	s_add_i32 s87, 16, 0x14000
	s_add_i32 s76, s76, s25
	v_add_u32_e32 v149, s87, v146
	v_lshl_add_u64 v[230:231], s[36:37], 0, v[130:131]
	s_mov_b32 m0, s76
	ds_read_b128 v[214:217], v149
	ds_read_b128 v[218:221], v149 offset:1024
	ds_read_b128 v[222:225], v149 offset:2048
	ds_read_b128 v[226:229], v149 offset:3072
	global_load_lds_dwordx4 v[230:231], off
	v_lshl_add_u64 v[232:233], s[36:37], 0, v[128:129]
	s_add_i32 m0, s76, 0x2000
	s_nop 0
	global_load_lds_dwordx4 v[232:233], off
	s_barrier
	s_waitcnt lgkmcnt(0)
	s_setprio 1
	s_waitcnt lgkmcnt(0)
	v_mfma_f32_16x16x32_bf16 v[116:119], v[214:217], v[158:161], v[116:119]
	v_mfma_f32_16x16x32_bf16 v[108:111], v[222:225], v[158:161], v[108:111]
	v_mfma_f32_16x16x32_bf16 v[100:103], v[214:217], v[166:169], v[100:103]
	v_mfma_f32_16x16x32_bf16 v[92:95], v[222:225], v[166:169], v[92:95]
	v_mfma_f32_16x16x32_bf16 v[84:87], v[214:217], v[174:177], v[84:87]
	v_mfma_f32_16x16x32_bf16 v[76:79], v[222:225], v[174:177], v[76:79]
	v_mfma_f32_16x16x32_bf16 v[68:71], v[214:217], v[182:185], v[68:71]
	v_mfma_f32_16x16x32_bf16 v[64:67], v[222:225], v[182:185], v[64:67]
	v_mfma_f32_16x16x32_bf16 v[116:119], v[218:221], v[162:165], v[116:119]
	v_mfma_f32_16x16x32_bf16 v[108:111], v[226:229], v[162:165], v[108:111]
	v_mfma_f32_16x16x32_bf16 v[100:103], v[218:221], v[170:173], v[100:103]
	v_mfma_f32_16x16x32_bf16 v[92:95], v[226:229], v[170:173], v[92:95]
	v_mfma_f32_16x16x32_bf16 v[84:87], v[218:221], v[178:181], v[84:87]
	v_mfma_f32_16x16x32_bf16 v[76:79], v[226:229], v[178:181], v[76:79]
	v_mfma_f32_16x16x32_bf16 v[68:71], v[218:221], v[198:201], v[68:71]
	v_mfma_f32_16x16x32_bf16 v[64:67], v[226:229], v[198:201], v[64:67]
	s_setprio 0
	s_mov_b32 m0, s48
	v_lshl_add_u64 v[234:235], s[38:39], 0, v[130:131]
	s_barrier
	ds_read_b128 v[158:161], v148 offset:16384
	ds_read_b128 v[162:165], v148 offset:17408
	ds_read_b128 v[166:169], v148 offset:18432
	ds_read_b128 v[170:173], v148 offset:19456
	ds_read_b128 v[174:177], v148 offset:20480
	ds_read_b128 v[178:181], v148 offset:21504
	ds_read_b128 v[182:185], v148 offset:22528
	ds_read_b128 v[198:201], v148 offset:23552
	global_load_lds_dwordx4 v[234:235], off
	v_lshl_add_u64 v[236:237], s[38:39], 0, v[128:129]
	s_mov_b32 m0, s49
	s_nop 0
	global_load_lds_dwordx4 v[236:237], off
	s_barrier
	s_waitcnt lgkmcnt(0)
	s_setprio 1
	s_waitcnt lgkmcnt(0)
	v_mfma_f32_16x16x32_bf16 v[60:63], v[136:139], v[158:161], v[60:63]
	v_mfma_f32_16x16x32_bf16 v[56:59], v[150:153], v[158:161], v[56:59]
	v_mfma_f32_16x16x32_bf16 v[48:51], v[136:139], v[166:169], v[48:51]
	v_mfma_f32_16x16x32_bf16 v[40:43], v[150:153], v[166:169], v[40:43]
	v_mfma_f32_16x16x32_bf16 v[32:35], v[136:139], v[174:177], v[32:35]
	v_mfma_f32_16x16x32_bf16 v[24:27], v[150:153], v[174:177], v[24:27]
	v_mfma_f32_16x16x32_bf16 v[16:19], v[136:139], v[182:185], v[16:19]
	v_mfma_f32_16x16x32_bf16 v[8:11], v[150:153], v[182:185], v[8:11]
	v_mfma_f32_16x16x32_bf16 v[60:63], v[140:143], v[162:165], v[60:63]
	v_mfma_f32_16x16x32_bf16 v[56:59], v[154:157], v[162:165], v[56:59]
	v_mfma_f32_16x16x32_bf16 v[48:51], v[140:143], v[170:173], v[48:51]
	v_mfma_f32_16x16x32_bf16 v[40:43], v[154:157], v[170:173], v[40:43]
	v_mfma_f32_16x16x32_bf16 v[32:35], v[140:143], v[178:181], v[32:35]
	v_mfma_f32_16x16x32_bf16 v[24:27], v[154:157], v[178:181], v[24:27]
	v_mfma_f32_16x16x32_bf16 v[16:19], v[140:143], v[198:201], v[16:19]
	v_mfma_f32_16x16x32_bf16 v[8:11], v[154:157], v[198:201], v[8:11]
	s_setprio 0
	s_barrier
; #define PG8_STAGE(bufoff, gbase, voff) do { _Pragma("unroll") for (int _i = 0; _i < 2; ++_i) \
;     __builtin_amdgcn_global_load_lds((const unsigned*)((const char*)(gbase) + (voff)[_i]), (LAS unsigned*)(lds + (bufoff) + ldsw + _i * 8192), 16, 0, 0); } while (0)
; #define PG8_LDA(dst, b, h) do { _Pragma("unroll") for (int m = 0; m < 4; ++m) _Pragma("unroll") for (int k = 0; k < 2; ++k) dst[m][k] = *(const LAS bf16x8*)(lds + PG8_SA(b, h) + aoff + m * 2048 + k * 1024); } while (0)
; #define PG8_LDB(dst, b, h) do { _Pragma("unroll") for (int n = 0; n < 2; ++n) _Pragma("unroll") for (int k = 0; k < 2; ++k) dst[n][k] = *(const LAS bf16x8*)(lds + PG8_SB(b, h) + boff + n * 2048 + k * 1024); } while (0)
; #define PG8_MMA(ai, bj, At, Bt) do { __builtin_amdgcn_s_setprio(1); _Pragma("unroll") for (int m = 0; m < 4; ++m) _Pragma("unroll") for (int n = 0; n < 2; ++n) _Pragma("unroll") for (int k = 0; k < 2; ++k) \
;     acc[ai][bj][m][n] = __builtin_amdgcn_mfma_f32_16x16x32_bf16(Bt[n][k], At[m][k], acc[ai][bj][m][n], 0, 0, 0); __builtin_amdgcn_s_setprio(0); } while (0)
; #define PG8_WAIT_V(n) asm volatile("s_waitcnt vmcnt(" #n ")" ::: "memory")
; #define PG8_WAIT_L(n) asm volatile("s_waitcnt lgkmcnt(" #n ")" ::: "memory")
; #define PG8_BAR __builtin_amdgcn_s_barrier()
; #define PG8_SCHED __builtin_amdgcn_sched_barrier(0)
; template <class Epi, class Sched>
; __device__ __forceinline__ void gemm_phase(LAS unsigned char* lds, const Gemm g, const Sched& S, const Epi& E) {
;     ...
;       PG8_LDA(At, 0, 1); PG8_STAGE(PG8_SA(0, 0), a2, voffA);
;       PG8_BAR; PG8_WAIT_L(0); PG8_MMA(1, 0, At, B0); PG8_BAR; PG8_SCHED;
;       PG8_STAGE(PG8_SB(0, 1), b2 + hstepB, voffB);
;       PG8_WAIT_V(6); PG8_BAR; PG8_MMA(1, 1, At, B1); PG8_BAR;
;       PG8_LDB(B0, 1, 0); PG8_SCHED; PG8_LDA(At, 1, 0); PG8_STAGE(PG8_SA(0, 1), a2 + hstepA, voffA);
;       PG8_WAIT_L(8); PG8_BAR; PG8_WAIT_L(0); PG8_MMA(0, 0, At, B0); PG8_BAR; PG8_SCHED;
;       PG8_LDB(B1, 1, 1); PG8_STAGE(PG8_SB(1, 0), b3, voffB);
;       PG8_BAR; PG8_WAIT_L(0); PG8_MMA(0, 1, At, B1); PG8_BAR;
;       PG8_LDA(At, 1, 1); PG8_STAGE(PG8_SA(1, 0), a3, voffA);
;       PG8_BAR; PG8_WAIT_L(0); PG8_MMA(1, 0, At, B0); PG8_BAR; PG8_SCHED;
	s_add_u32 s76, s36, 0x40000
	s_addc_u32 s77, s37, 0
	s_add_i32 s87, s87, s25
	v_lshl_add_u64 v[136:137], s[76:77], 0, v[130:131]
	s_mov_b32 m0, s87
	s_nop 0
	global_load_lds_dwordx4 v[136:137], off
	v_lshl_add_u64 v[136:137], s[76:77], 0, v[128:129]
	s_add_i32 m0, s87, 0x2000
	s_nop 0
	global_load_lds_dwordx4 v[136:137], off
	s_waitcnt vmcnt(6)
	s_barrier
	s_setprio 1
	v_mfma_f32_16x16x32_bf16 v[52:55], v[214:217], v[158:161], v[52:55]
	v_mfma_f32_16x16x32_bf16 v[44:47], v[222:225], v[158:161], v[44:47]
	v_mfma_f32_16x16x32_bf16 v[36:39], v[214:217], v[166:169], v[36:39]
	v_mfma_f32_16x16x32_bf16 v[28:31], v[222:225], v[166:169], v[28:31]
	v_mfma_f32_16x16x32_bf16 v[20:23], v[214:217], v[174:177], v[20:23]
	v_mfma_f32_16x16x32_bf16 v[12:15], v[222:225], v[174:177], v[12:15]
	v_mfma_f32_16x16x32_bf16 v[4:7], v[214:217], v[182:185], v[4:7]
	v_mfma_f32_16x16x32_bf16 v[0:3], v[222:225], v[182:185], v[0:3]
	v_mfma_f32_16x16x32_bf16 v[52:55], v[218:221], v[162:165], v[52:55]
	v_mfma_f32_16x16x32_bf16 v[44:47], v[226:229], v[162:165], v[44:47]
	v_mfma_f32_16x16x32_bf16 v[36:39], v[218:221], v[170:173], v[36:39]
	v_mfma_f32_16x16x32_bf16 v[28:31], v[226:229], v[170:173], v[28:31]
	v_mfma_f32_16x16x32_bf16 v[20:23], v[218:221], v[178:181], v[20:23]
	v_mfma_f32_16x16x32_bf16 v[12:15], v[226:229], v[178:181], v[12:15]
	v_mfma_f32_16x16x32_bf16 v[4:7], v[218:221], v[198:201], v[4:7]
	v_mfma_f32_16x16x32_bf16 v[0:3], v[226:229], v[198:201], v[0:3]
	s_setprio 0
	s_add_i32 s76, 16, 0x18000
	v_add_u32_e32 v149, s76, v146
	s_barrier
	ds_read_b128 v[136:139], v149
	ds_read_b128 v[140:143], v149 offset:1024
	ds_read_b128 v[150:153], v149 offset:2048
	ds_read_b128 v[154:157], v149 offset:3072
	s_add_u32 s38, s38, 0x40000
	s_addc_u32 s39, s39, 0
	s_mov_b32 m0, s51
	v_lshl_add_u64 v[214:215], s[38:39], 0, v[130:131]
	ds_read_b128 v[158:161], v148 offset:32768
	ds_read_b128 v[162:165], v148 offset:33792
	ds_read_b128 v[166:169], v148 offset:34816
	ds_read_b128 v[170:173], v148 offset:35840
	ds_read_b128 v[174:177], v148 offset:36864
	ds_read_b128 v[178:181], v148 offset:37888
	ds_read_b128 v[182:185], v148 offset:38912
	ds_read_b128 v[198:201], v148 offset:39936
	global_load_lds_dwordx4 v[214:215], off
	v_lshl_add_u64 v[214:215], s[38:39], 0, v[128:129]
	s_mov_b32 m0, s58
	s_nop 0
	global_load_lds_dwordx4 v[214:215], off
	s_waitcnt lgkmcnt(8)
	s_barrier
	s_waitcnt lgkmcnt(0)
	s_setprio 1
	s_waitcnt lgkmcnt(0)
	v_mfma_f32_16x16x32_bf16 v[124:127], v[136:139], v[158:161], v[124:127]
	v_mfma_f32_16x16x32_bf16 v[120:123], v[150:153], v[158:161], v[120:123]
	v_mfma_f32_16x16x32_bf16 v[112:115], v[136:139], v[166:169], v[112:115]
	v_mfma_f32_16x16x32_bf16 v[104:107], v[150:153], v[166:169], v[104:107]
	v_mfma_f32_16x16x32_bf16 v[96:99], v[136:139], v[174:177], v[96:99]
	v_mfma_f32_16x16x32_bf16 v[88:91], v[150:153], v[174:177], v[88:91]
	v_mfma_f32_16x16x32_bf16 v[80:83], v[136:139], v[182:185], v[80:83]
	v_mfma_f32_16x16x32_bf16 v[72:75], v[150:153], v[182:185], v[72:75]
	v_mfma_f32_16x16x32_bf16 v[124:127], v[140:143], v[162:165], v[124:127]
	v_mfma_f32_16x16x32_bf16 v[120:123], v[154:157], v[162:165], v[120:123]
	v_mfma_f32_16x16x32_bf16 v[112:115], v[140:143], v[170:173], v[112:115]
	v_mfma_f32_16x16x32_bf16 v[104:107], v[154:157], v[170:173], v[104:107]
	v_mfma_f32_16x16x32_bf16 v[96:99], v[140:143], v[178:181], v[96:99]
	v_mfma_f32_16x16x32_bf16 v[88:91], v[154:157], v[178:181], v[88:91]
	v_mfma_f32_16x16x32_bf16 v[80:83], v[140:143], v[198:201], v[80:83]
	v_mfma_f32_16x16x32_bf16 v[72:75], v[154:157], v[198:201], v[72:75]
	s_setprio 0
	s_barrier
	s_add_i32 s38, 16, 0x1c000
	s_add_i32 s39, s76, s25
	v_add_u32_e32 v149, s38, v146
	v_lshl_add_u64 v[230:231], v[230:231], 0, s[62:63]
	s_mov_b32 m0, s39
	ds_read_b128 v[214:217], v149
	ds_read_b128 v[218:221], v149 offset:1024
	ds_read_b128 v[222:225], v149 offset:2048
	ds_read_b128 v[226:229], v149 offset:3072
	global_load_lds_dwordx4 v[230:231], off
	v_lshl_add_u64 v[230:231], v[232:233], 0, s[62:63]
	s_add_i32 m0, s39, 0x2000
	s_nop 0
	global_load_lds_dwordx4 v[230:231], off
	s_barrier
	s_waitcnt lgkmcnt(0)
	s_setprio 1
	s_waitcnt lgkmcnt(0)
	v_mfma_f32_16x16x32_bf16 v[116:119], v[214:217], v[158:161], v[116:119]
	v_mfma_f32_16x16x32_bf16 v[108:111], v[222:225], v[158:161], v[108:111]
	v_mfma_f32_16x16x32_bf16 v[100:103], v[214:217], v[166:169], v[100:103]
	v_mfma_f32_16x16x32_bf16 v[92:95], v[222:225], v[166:169], v[92:95]
	v_mfma_f32_16x16x32_bf16 v[84:87], v[214:217], v[174:177], v[84:87]
	v_mfma_f32_16x16x32_bf16 v[76:79], v[222:225], v[174:177], v[76:79]
	v_mfma_f32_16x16x32_bf16 v[68:71], v[214:217], v[182:185], v[68:71]
	v_mfma_f32_16x16x32_bf16 v[64:67], v[222:225], v[182:185], v[64:67]
	v_mfma_f32_16x16x32_bf16 v[116:119], v[218:221], v[162:165], v[116:119]
	v_mfma_f32_16x16x32_bf16 v[108:111], v[226:229], v[162:165], v[108:111]
	v_mfma_f32_16x16x32_bf16 v[100:103], v[218:221], v[170:173], v[100:103]
	v_mfma_f32_16x16x32_bf16 v[92:95], v[226:229], v[170:173], v[92:95]
	v_mfma_f32_16x16x32_bf16 v[84:87], v[218:221], v[178:181], v[84:87]
	v_mfma_f32_16x16x32_bf16 v[76:79], v[226:229], v[178:181], v[76:79]
	v_mfma_f32_16x16x32_bf16 v[68:71], v[218:221], v[198:201], v[68:71]
	v_mfma_f32_16x16x32_bf16 v[64:67], v[226:229], v[198:201], v[64:67]
	s_setprio 0
	s_mov_b32 m0, s69
	v_lshl_add_u64 v[230:231], v[234:235], 0, s[62:63]
	s_barrier
	ds_read_b128 v[158:161], v148 offset:49152
	ds_read_b128 v[162:165], v148 offset:50176
	ds_read_b128 v[166:169], v148 offset:51200
	ds_read_b128 v[170:173], v148 offset:52224
	ds_read_b128 v[174:177], v148 offset:53248
	ds_read_b128 v[178:181], v148 offset:54272
	ds_read_b128 v[182:185], v148 offset:55296
	ds_read_b128 v[198:201], v148 offset:56320
	global_load_lds_dwordx4 v[230:231], off
	v_lshl_add_u64 v[230:231], v[236:237], 0, s[62:63]
	s_mov_b32 m0, s74
	s_nop 0
	global_load_lds_dwordx4 v[230:231], off
	s_barrier
; #define PG8_STAGE(bufoff, gbase, voff) do { _Pragma("unroll") for (int _i = 0; _i < 2; ++_i) \
;     __builtin_amdgcn_global_load_lds((const unsigned*)((const char*)(gbase) + (voff)[_i]), (LAS unsigned*)(lds + (bufoff) + ldsw + _i * 8192), 16, 0, 0); } while (0)
; #define PG8_LDA(dst, b, h) do { _Pragma("unroll") for (int m = 0; m < 4; ++m) _Pragma("unroll") for (int k = 0; k < 2; ++k) dst[m][k] = *(const LAS bf16x8*)(lds + PG8_SA(b, h) + aoff + m * 2048 + k * 1024); } while (0)
; #define PG8_LDB(dst, b, h) do { _Pragma("unroll") for (int n = 0; n < 2; ++n) _Pragma("unroll") for (int k = 0; k < 2; ++k) dst[n][k] = *(const LAS bf16x8*)(lds + PG8_SB(b, h) + boff + n * 2048 + k * 1024); } while (0)
; #define PG8_MMA(ai, bj, At, Bt) do { __builtin_amdgcn_s_setprio(1); _Pragma("unroll") for (int m = 0; m < 4; ++m) _Pragma("unroll") for (int n = 0; n < 2; ++n) _Pragma("unroll") for (int k = 0; k < 2; ++k) \
;     acc[ai][bj][m][n] = __builtin_amdgcn_mfma_f32_16x16x32_bf16(Bt[n][k], At[m][k], acc[ai][bj][m][n], 0, 0, 0); __builtin_amdgcn_s_setprio(0); } while (0)
; #define PG8_WAIT_V(n) asm volatile("s_waitcnt vmcnt(" #n ")" ::: "memory")
; #define PG8_WAIT_L(n) asm volatile("s_waitcnt lgkmcnt(" #n ")" ::: "memory")
; #define PG8_BAR __builtin_amdgcn_s_barrier()
; #define PG8_SCHED __builtin_amdgcn_sched_barrier(0)
; template <class Epi, class Sched>
; __device__ __forceinline__ void gemm_phase(LAS unsigned char* lds, const Gemm g, const Sched& S, const Epi& E) {
;     ...
;       PG8_WAIT_V(6); PG8_BAR; PG8_MMA(1, 1, At, B1); PG8_BAR;
;       PG8_LDB(B0, 1, 0); PG8_SCHED; PG8_LDA(At, 1, 0); PG8_STAGE(PG8_SA(0, 1), a2 + hstepA, voffA);
;       PG8_WAIT_L(8); PG8_BAR; PG8_WAIT_L(0); PG8_MMA(0, 0, At, B0); PG8_BAR; PG8_SCHED;
;       PG8_LDB(B1, 1, 1); PG8_STAGE(PG8_SB(1, 0), b3, voffB);
;       PG8_BAR; PG8_WAIT_L(0); PG8_MMA(0, 1, At, B1); PG8_BAR;
;       PG8_LDA(At, 1, 1); PG8_STAGE(PG8_SA(1, 0), a3, voffA);
;       PG8_BAR; PG8_WAIT_L(0); PG8_MMA(1, 0, At, B0); PG8_BAR; PG8_SCHED;
;       PG8_STAGE(PG8_SB(1, 1), b3 + hstepB, voffB);
;       PG8_WAIT_V(6); PG8_BAR; PG8_MMA(1, 1, At, B1); PG8_BAR;
	s_waitcnt lgkmcnt(0)
	s_setprio 1
	s_waitcnt lgkmcnt(0)
	v_mfma_f32_16x16x32_bf16 v[60:63], v[136:139], v[158:161], v[60:63]
	v_mfma_f32_16x16x32_bf16 v[56:59], v[150:153], v[158:161], v[56:59]
	v_mfma_f32_16x16x32_bf16 v[48:51], v[136:139], v[166:169], v[48:51]
	v_mfma_f32_16x16x32_bf16 v[40:43], v[150:153], v[166:169], v[40:43]
	v_mfma_f32_16x16x32_bf16 v[32:35], v[136:139], v[174:177], v[32:35]
	v_mfma_f32_16x16x32_bf16 v[24:27], v[150:153], v[174:177], v[24:27]
	v_mfma_f32_16x16x32_bf16 v[16:19], v[136:139], v[182:185], v[16:19]
	v_mfma_f32_16x16x32_bf16 v[8:11], v[150:153], v[182:185], v[8:11]
	v_mfma_f32_16x16x32_bf16 v[60:63], v[140:143], v[162:165], v[60:63]
	v_mfma_f32_16x16x32_bf16 v[56:59], v[154:157], v[162:165], v[56:59]
	v_mfma_f32_16x16x32_bf16 v[48:51], v[140:143], v[170:173], v[48:51]
	v_mfma_f32_16x16x32_bf16 v[40:43], v[154:157], v[170:173], v[40:43]
	v_mfma_f32_16x16x32_bf16 v[32:35], v[140:143], v[178:181], v[32:35]
	v_mfma_f32_16x16x32_bf16 v[24:27], v[154:157], v[178:181], v[24:27]
	v_mfma_f32_16x16x32_bf16 v[16:19], v[140:143], v[198:201], v[16:19]
	v_mfma_f32_16x16x32_bf16 v[8:11], v[154:157], v[198:201], v[8:11]
	s_setprio 0
	s_barrier
	s_add_u32 s36, s36, 0x40080
	s_addc_u32 s37, s37, 0
	s_add_i32 s38, s38, s25
	v_lshl_add_u64 v[136:137], s[36:37], 0, v[130:131]
	s_mov_b32 m0, s38
	s_nop 0
	global_load_lds_dwordx4 v[136:137], off
	v_lshl_add_u64 v[136:137], s[36:37], 0, v[128:129]
	s_add_i32 m0, s38, 0x2000
	s_nop 0
	global_load_lds_dwordx4 v[136:137], off
	s_waitcnt vmcnt(6)
	s_barrier
	s_setprio 1
	v_mfma_f32_16x16x32_bf16 v[52:55], v[214:217], v[158:161], v[52:55]
	v_mfma_f32_16x16x32_bf16 v[44:47], v[222:225], v[158:161], v[44:47]
	v_mfma_f32_16x16x32_bf16 v[36:39], v[214:217], v[166:169], v[36:39]
	v_mfma_f32_16x16x32_bf16 v[28:31], v[222:225], v[166:169], v[28:31]
	v_mfma_f32_16x16x32_bf16 v[20:23], v[214:217], v[174:177], v[20:23]
	v_mfma_f32_16x16x32_bf16 v[12:15], v[222:225], v[174:177], v[12:15]
	v_mfma_f32_16x16x32_bf16 v[4:7], v[214:217], v[182:185], v[4:7]
	v_mfma_f32_16x16x32_bf16 v[0:3], v[222:225], v[182:185], v[0:3]
	v_mfma_f32_16x16x32_bf16 v[52:55], v[218:221], v[162:165], v[52:55]
	v_mfma_f32_16x16x32_bf16 v[44:47], v[226:229], v[162:165], v[44:47]
	v_mfma_f32_16x16x32_bf16 v[36:39], v[218:221], v[170:173], v[36:39]
	v_mfma_f32_16x16x32_bf16 v[28:31], v[226:229], v[170:173], v[28:31]
	v_mfma_f32_16x16x32_bf16 v[20:23], v[218:221], v[178:181], v[20:23]
	v_mfma_f32_16x16x32_bf16 v[12:15], v[226:229], v[178:181], v[12:15]
	v_mfma_f32_16x16x32_bf16 v[4:7], v[218:221], v[198:201], v[4:7]
	v_mfma_f32_16x16x32_bf16 v[0:3], v[226:229], v[198:201], v[0:3]
	s_setprio 0
	s_add_i32 s86, s86, 2
	s_add_u32 s28, s28, 0x100
	s_addc_u32 s29, s29, 0
	s_add_u32 s84, s84, 0x100
	s_addc_u32 s85, s85, 0
	s_cmp_gt_u32 s86, 13
	s_barrier
	s_cbranch_scc0 .LBB0_2633
	v_lshl_add_u32 v140, s79, 8, v145
	v_lshl_or_b32 v136, s78, 8, v147
	v_ashrrev_i32_e32 v141, 31, v140
	v_lshlrev_b64 v[138:139], 12, v[140:141]
	v_ashrrev_i32_e32 v137, 31, v136
	v_lshlrev_b64 v[142:143], 2, v[136:137]
	v_lshl_add_u64 v[136:137], s[14:15], 0, v[138:139]
	v_lshl_add_u64 v[138:139], s[16:17], 0, v[138:139]
	s_mov_b32 s28, 0xfff00000
	v_mov_b32_e32 v141, s66
	v_mov_b32_e32 v149, s68
	v_cmp_gt_i32_e32 vcc, s73, v140
	v_mov_b32_e32 v150, s59
	v_mov_b32_e32 v151, s67
	v_lshl_add_u64 v[138:139], v[138:139], 0, v[142:143]
	s_mov_b32 s29, -1
	v_cndmask_b32_e32 v153, v141, v149, vcc
	v_cndmask_b32_e32 v152, v150, v151, vcc
	v_lshl_add_u64 v[136:137], v[136:137], 0, v[142:143]
	v_lshl_add_u64 v[156:157], v[138:139], 0, s[28:29]
	v_lshl_add_u64 v[160:161], v[152:153], 0, v[142:143]
	v_cndmask_b32_e64 v163, v157, v137, s[8:9]
	v_cndmask_b32_e64 v162, v156, v136, s[8:9]
	global_load_dwordx4 v[214:217], v[160:161], off
	global_load_dwordx4 v[218:221], v[160:161], off offset:64
	global_load_dwordx4 v[222:225], v[160:161], off offset:512
	global_load_dwordx4 v[226:229], v[160:161], off offset:576
	global_load_dwordx4 v[230:233], v[162:163], off
	global_load_dwordx4 v[234:237], v[162:163], off offset:64
	global_load_dwordx4 v[238:241], v[162:163], off offset:512
	global_load_dwordx4 v[242:245], v[162:163], off offset:576
	s_mov_b32 s28, 0xfff10000
	s_mov_b32 s29, -1
	s_movk_i32 s19, 0x80
	s_mov_b32 s87, 0x80000
	s_mov_b32 s78, s18
	s_mov_b32 s79, s20
	s_mov_b64 s[36:37], s[26:27]
	s_movk_i32 s86, 0x4100
	s_waitcnt vmcnt(3)
	v_pk_fma_f32 v[126:127], v[126:127], v[216:217], v[232:233]
	v_pk_fma_f32 v[124:125], v[124:125], v[214:215], v[230:231]
	global_store_dwordx4 v[136:137], v[124:127], off
	s_nop 0
	s_waitcnt vmcnt(3)
	v_pk_fma_f32 v[122:123], v[122:123], v[220:221], v[236:237]
	v_pk_fma_f32 v[120:121], v[120:121], v[218:219], v[234:235]
	global_store_dwordx4 v[136:137], v[120:123], off offset:64
	s_nop 0
	v_lshl_add_u64 v[152:153], v[138:139], 0, s[28:29]
	s_mov_b32 s28, 0xfff20000
	s_mov_b32 s29, -1
	s_waitcnt vmcnt(3)
	v_pk_fma_f32 v[118:119], v[118:119], v[224:225], v[240:241]
	v_pk_fma_f32 v[116:117], v[116:117], v[222:223], v[238:239]
	global_store_dwordx4 v[136:137], v[116:119], off offset:512
	s_nop 0
	v_or_b32_e32 v124, 16, v140
	v_ashrrev_i32_e32 v125, 31, v124
	v_cmp_gt_i32_e32 vcc, s73, v124
	v_lshlrev_b64 v[124:125], 12, v[124:125]
	v_lshl_add_u64 v[124:125], s[14:15], 0, v[124:125]
	v_cndmask_b32_e32 v127, v141, v149, vcc
	v_cndmask_b32_e32 v126, v150, v151, vcc
	v_lshl_add_u64 v[126:127], v[126:127], 0, v[142:143]
	v_lshl_add_u64 v[124:125], v[124:125], 0, v[142:143]
	v_cndmask_b32_e64 v153, v153, v125, s[8:9]
	v_cndmask_b32_e64 v152, v152, v124, s[8:9]
	s_waitcnt vmcnt(3)
	v_pk_fma_f32 v[110:111], v[110:111], v[228:229], v[244:245]
	v_pk_fma_f32 v[108:109], v[108:109], v[226:227], v[242:243]
	global_store_dwordx4 v[136:137], v[108:111], off offset:576
	global_load_dwordx4 v[214:217], v[126:127], off
	global_load_dwordx4 v[218:221], v[126:127], off offset:64
	global_load_dwordx4 v[222:225], v[126:127], off offset:512
	global_load_dwordx4 v[226:229], v[126:127], off offset:576
	global_load_dwordx4 v[230:233], v[152:153], off
	global_load_dwordx4 v[234:237], v[152:153], off offset:64
	global_load_dwordx4 v[238:241], v[152:153], off offset:512
	global_load_dwordx4 v[242:245], v[152:153], off offset:576
	s_nop 0
	s_waitcnt vmcnt(3)
	v_pk_fma_f32 v[110:111], v[114:115], v[216:217], v[232:233]
	v_pk_fma_f32 v[108:109], v[112:113], v[214:215], v[230:231]
	global_store_dwordx4 v[124:125], v[108:111], off
	s_nop 0
	s_waitcnt vmcnt(3)
	v_pk_fma_f32 v[106:107], v[106:107], v[220:221], v[236:237]
	v_pk_fma_f32 v[104:105], v[104:105], v[218:219], v[234:235]
	global_store_dwordx4 v[124:125], v[104:107], off offset:64
	s_nop 0
	v_lshl_add_u64 v[112:113], v[138:139], 0, s[28:29]
	s_mov_b32 s28, 0xfff30000
	s_mov_b32 s29, -1
	s_waitcnt vmcnt(3)
	v_pk_fma_f32 v[102:103], v[102:103], v[224:225], v[240:241]
	v_pk_fma_f32 v[100:101], v[100:101], v[222:223], v[238:239]
	global_store_dwordx4 v[124:125], v[100:103], off offset:512
	s_nop 0
	v_or_b32_e32 v108, 32, v140
	v_ashrrev_i32_e32 v109, 31, v108
	v_cmp_gt_i32_e32 vcc, s73, v108
	v_lshlrev_b64 v[108:109], 12, v[108:109]
	v_lshl_add_u64 v[108:109], s[14:15], 0, v[108:109]
	v_cndmask_b32_e32 v111, v141, v149, vcc
	v_cndmask_b32_e32 v110, v150, v151, vcc
	v_lshl_add_u64 v[110:111], v[110:111], 0, v[142:143]
	v_lshl_add_u64 v[108:109], v[108:109], 0, v[142:143]
	v_cndmask_b32_e64 v113, v113, v109, s[8:9]
	v_cndmask_b32_e64 v112, v112, v108, s[8:9]
	s_waitcnt vmcnt(3)
	v_pk_fma_f32 v[94:95], v[94:95], v[228:229], v[244:245]
	v_pk_fma_f32 v[92:93], v[92:93], v[226:227], v[242:243]
	global_store_dwordx4 v[124:125], v[92:95], off offset:576
	global_load_dwordx4 v[214:217], v[110:111], off
	global_load_dwordx4 v[218:221], v[110:111], off offset:64
	global_load_dwordx4 v[222:225], v[110:111], off offset:512
	global_load_dwordx4 v[226:229], v[110:111], off offset:576
	global_load_dwordx4 v[230:233], v[112:113], off
	global_load_dwordx4 v[234:237], v[112:113], off offset:64
	global_load_dwordx4 v[238:241], v[112:113], off offset:512
	global_load_dwordx4 v[242:245], v[112:113], off offset:576
	s_nop 0
	s_waitcnt vmcnt(3)
	v_pk_fma_f32 v[94:95], v[98:99], v[216:217], v[232:233]
	v_pk_fma_f32 v[92:93], v[96:97], v[214:215], v[230:231]
	global_store_dwordx4 v[108:109], v[92:95], off
	s_nop 0
	s_waitcnt vmcnt(3)
	v_pk_fma_f32 v[90:91], v[90:91], v[220:221], v[236:237]
	v_pk_fma_f32 v[88:89], v[88:89], v[218:219], v[234:235]
	global_store_dwordx4 v[108:109], v[88:91], off offset:64
	s_nop 0
	v_lshl_add_u64 v[96:97], v[138:139], 0, s[28:29]
	s_mov_b64 s[28:29], 0x80000
	s_waitcnt vmcnt(3)
	v_pk_fma_f32 v[86:87], v[86:87], v[224:225], v[240:241]
	v_pk_fma_f32 v[84:85], v[84:85], v[222:223], v[238:239]
	global_store_dwordx4 v[108:109], v[84:87], off offset:512
	s_nop 0
	v_or_b32_e32 v92, 48, v140
	v_ashrrev_i32_e32 v93, 31, v92
	v_cmp_gt_i32_e32 vcc, s73, v92
	v_lshlrev_b64 v[92:93], 12, v[92:93]
	v_lshl_add_u64 v[92:93], s[14:15], 0, v[92:93]
	v_cndmask_b32_e32 v95, v141, v149, vcc
	v_cndmask_b32_e32 v94, v150, v151, vcc
	v_lshl_add_u64 v[94:95], v[94:95], 0, v[142:143]
	v_lshl_add_u64 v[92:93], v[92:93], 0, v[142:143]
	v_cndmask_b32_e64 v97, v97, v93, s[8:9]
	v_cndmask_b32_e64 v96, v96, v92, s[8:9]
	v_cmp_gt_i32_e32 vcc, s19, v140
	s_mov_b32 s19, 0x90000
	s_waitcnt vmcnt(3)
	v_pk_fma_f32 v[78:79], v[78:79], v[228:229], v[244:245]
	v_pk_fma_f32 v[76:77], v[76:77], v[226:227], v[242:243]
	global_store_dwordx4 v[108:109], v[76:79], off offset:576
	global_load_dwordx4 v[214:217], v[94:95], off
	global_load_dwordx4 v[218:221], v[94:95], off offset:64
	global_load_dwordx4 v[222:225], v[94:95], off offset:512
	global_load_dwordx4 v[226:229], v[94:95], off offset:576
	global_load_dwordx4 v[230:233], v[96:97], off
	global_load_dwordx4 v[234:237], v[96:97], off offset:64
	global_load_dwordx4 v[238:241], v[96:97], off offset:512
	global_load_dwordx4 v[242:245], v[96:97], off offset:576
	s_nop 0
	s_waitcnt vmcnt(3)
	v_pk_fma_f32 v[78:79], v[82:83], v[216:217], v[232:233]
	v_pk_fma_f32 v[76:77], v[80:81], v[214:215], v[230:231]
	global_store_dwordx4 v[92:93], v[76:79], off
	s_nop 0
	s_waitcnt vmcnt(3)
	v_pk_fma_f32 v[74:75], v[74:75], v[220:221], v[236:237]
	v_pk_fma_f32 v[72:73], v[72:73], v[218:219], v[234:235]
	global_store_dwordx4 v[92:93], v[72:75], off offset:64
	s_nop 0
	s_waitcnt vmcnt(3)
	v_pk_fma_f32 v[70:71], v[70:71], v[224:225], v[240:241]
	v_pk_fma_f32 v[68:69], v[68:69], v[222:223], v[238:239]
	global_store_dwordx4 v[92:93], v[68:71], off offset:512
	s_nop 0
	v_lshl_add_u64 v[78:79], v[136:137], 0, s[28:29]
	s_mov_b32 s28, 0xfff80000
	v_cndmask_b32_e32 v77, v141, v149, vcc
	v_cndmask_b32_e32 v76, v150, v151, vcc
	s_mov_b32 s29, -1
	v_lshl_add_u64 v[76:77], v[76:77], 0, v[142:143]
	v_lshl_add_u64 v[80:81], v[138:139], 0, s[28:29]
	v_cndmask_b32_e64 v81, v81, v79, s[8:9]
	v_cndmask_b32_e64 v80, v80, v78, s[8:9]
	s_mov_b64 s[28:29], 0x90000
	s_waitcnt vmcnt(3)
	v_pk_fma_f32 v[66:67], v[66:67], v[228:229], v[244:245]
	v_pk_fma_f32 v[64:65], v[64:65], v[226:227], v[242:243]
	global_store_dwordx4 v[92:93], v[64:67], off offset:576
	global_load_dwordx4 v[214:217], v[76:77], off
	global_load_dwordx4 v[218:221], v[76:77], off offset:64
	global_load_dwordx4 v[222:225], v[76:77], off offset:512
	global_load_dwordx4 v[226:229], v[76:77], off offset:576
	global_load_dwordx4 v[230:233], v[80:81], off
	global_load_dwordx4 v[234:237], v[80:81], off offset:64
	global_load_dwordx4 v[238:241], v[80:81], off offset:512
	global_load_dwordx4 v[242:245], v[80:81], off offset:576
	s_nop 0
	v_add_co_u32_e32 v72, vcc, s87, v136
	s_waitcnt vmcnt(3)
	v_pk_fma_f32 v[62:63], v[62:63], v[216:217], v[232:233]
	v_addc_co_u32_e32 v73, vcc, 0, v137, vcc
	v_pk_fma_f32 v[60:61], v[60:61], v[214:215], v[230:231]
	global_store_dwordx4 v[72:73], v[60:63], off
	s_nop 0
	v_cmp_gt_i32_e32 vcc, s40, v140
	s_waitcnt vmcnt(3)
	v_pk_fma_f32 v[58:59], v[58:59], v[220:221], v[236:237]
	v_pk_fma_f32 v[56:57], v[56:57], v[218:219], v[234:235]
	global_store_dwordx4 v[78:79], v[56:59], off offset:64
	s_nop 0
	s_waitcnt vmcnt(3)
	v_pk_fma_f32 v[54:55], v[54:55], v[224:225], v[240:241]
	v_pk_fma_f32 v[52:53], v[52:53], v[222:223], v[238:239]
	global_store_dwordx4 v[78:79], v[52:55], off offset:512
	s_nop 0
	v_lshl_add_u64 v[62:63], v[136:137], 0, s[28:29]
	s_mov_b32 s28, 0xfff90000
	v_cndmask_b32_e32 v61, v141, v149, vcc
	v_cndmask_b32_e32 v60, v150, v151, vcc
	s_mov_b32 s29, -1
	v_lshl_add_u64 v[60:61], v[60:61], 0, v[142:143]
	v_lshl_add_u64 v[64:65], v[138:139], 0, s[28:29]
	v_cndmask_b32_e64 v65, v65, v63, s[8:9]
	v_cndmask_b32_e64 v64, v64, v62, s[8:9]
	s_mov_b64 s[28:29], 0xa0000
	s_waitcnt vmcnt(3)
	v_pk_fma_f32 v[46:47], v[46:47], v[228:229], v[244:245]
	v_pk_fma_f32 v[44:45], v[44:45], v[226:227], v[242:243]
	global_store_dwordx4 v[78:79], v[44:47], off offset:576
	global_load_dwordx4 v[214:217], v[60:61], off
	global_load_dwordx4 v[218:221], v[60:61], off offset:64
	global_load_dwordx4 v[222:225], v[60:61], off offset:512
	global_load_dwordx4 v[226:229], v[60:61], off offset:576
	global_load_dwordx4 v[230:233], v[64:65], off
	global_load_dwordx4 v[234:237], v[64:65], off offset:64
	global_load_dwordx4 v[238:241], v[64:65], off offset:512
	global_load_dwordx4 v[242:245], v[64:65], off offset:576
	s_nop 0
	v_add_co_u32_e32 v56, vcc, s19, v136
	s_mov_b32 s19, 0xa0000
	s_nop 0
	v_addc_co_u32_e32 v57, vcc, 0, v137, vcc
	v_cmp_gt_i32_e32 vcc, s91, v140
	s_waitcnt vmcnt(3)
	v_pk_fma_f32 v[46:47], v[50:51], v[216:217], v[232:233]
	v_pk_fma_f32 v[44:45], v[48:49], v[214:215], v[230:231]
	global_store_dwordx4 v[56:57], v[44:47], off
	s_nop 0
	s_waitcnt vmcnt(3)
	v_pk_fma_f32 v[42:43], v[42:43], v[220:221], v[236:237]
	v_pk_fma_f32 v[40:41], v[40:41], v[218:219], v[234:235]
	global_store_dwordx4 v[62:63], v[40:43], off offset:64
	s_nop 0
	s_waitcnt vmcnt(3)
	v_pk_fma_f32 v[38:39], v[38:39], v[224:225], v[240:241]
	v_pk_fma_f32 v[36:37], v[36:37], v[222:223], v[238:239]
	global_store_dwordx4 v[62:63], v[36:39], off offset:512
	s_nop 0
	v_lshl_add_u64 v[46:47], v[136:137], 0, s[28:29]
	s_mov_b32 s28, 0xfffa0000
	v_cndmask_b32_e32 v45, v141, v149, vcc
	v_cndmask_b32_e32 v44, v150, v151, vcc
	s_mov_b32 s29, -1
	v_lshl_add_u64 v[44:45], v[44:45], 0, v[142:143]
	v_lshl_add_u64 v[48:49], v[138:139], 0, s[28:29]
	v_cndmask_b32_e64 v49, v49, v47, s[8:9]
	v_cndmask_b32_e64 v48, v48, v46, s[8:9]
	s_mov_b64 s[28:29], 0xb0000
	s_waitcnt vmcnt(3)
	v_pk_fma_f32 v[30:31], v[30:31], v[228:229], v[244:245]
	v_pk_fma_f32 v[28:29], v[28:29], v[226:227], v[242:243]
	global_store_dwordx4 v[62:63], v[28:31], off offset:576
	global_load_dwordx4 v[214:217], v[44:45], off
	global_load_dwordx4 v[218:221], v[44:45], off offset:64
	global_load_dwordx4 v[222:225], v[44:45], off offset:512
	global_load_dwordx4 v[226:229], v[44:45], off offset:576
	global_load_dwordx4 v[230:233], v[48:49], off
	global_load_dwordx4 v[234:237], v[48:49], off offset:64
	global_load_dwordx4 v[238:241], v[48:49], off offset:512
	global_load_dwordx4 v[242:245], v[48:49], off offset:576
	s_nop 0
	v_add_co_u32_e32 v40, vcc, s19, v136
	s_mov_b32 s19, 0xb0000
	s_nop 0
	v_addc_co_u32_e32 v41, vcc, 0, v137, vcc
	v_cmp_gt_i32_e32 vcc, s41, v140
	s_waitcnt vmcnt(3)
	v_pk_fma_f32 v[30:31], v[34:35], v[216:217], v[232:233]
	v_pk_fma_f32 v[28:29], v[32:33], v[214:215], v[230:231]
	global_store_dwordx4 v[40:41], v[28:31], off
	s_nop 0
	s_waitcnt vmcnt(3)
	v_pk_fma_f32 v[26:27], v[26:27], v[220:221], v[236:237]
	v_pk_fma_f32 v[24:25], v[24:25], v[218:219], v[234:235]
	global_store_dwordx4 v[46:47], v[24:27], off offset:64
	s_nop 0
	s_waitcnt vmcnt(3)
	v_pk_fma_f32 v[22:23], v[22:23], v[224:225], v[240:241]
	v_pk_fma_f32 v[20:21], v[20:21], v[222:223], v[238:239]
	global_store_dwordx4 v[46:47], v[20:23], off offset:512
	s_nop 0
	v_lshl_add_u64 v[30:31], v[136:137], 0, s[28:29]
	s_mov_b32 s28, 0xfffb0000
	v_cndmask_b32_e32 v29, v141, v149, vcc
	v_cndmask_b32_e32 v28, v150, v151, vcc
	s_mov_b32 s29, -1
	v_lshl_add_u64 v[28:29], v[28:29], 0, v[142:143]
	v_lshl_add_u64 v[32:33], v[138:139], 0, s[28:29]
	v_cndmask_b32_e64 v33, v33, v31, s[8:9]
	v_cndmask_b32_e64 v32, v32, v30, s[8:9]
	s_mov_b64 s[28:29], s[22:23]
	s_waitcnt vmcnt(3)
	v_pk_fma_f32 v[14:15], v[14:15], v[228:229], v[244:245]
	v_pk_fma_f32 v[12:13], v[12:13], v[226:227], v[242:243]
	global_store_dwordx4 v[46:47], v[12:15], off offset:576
	global_load_dwordx4 v[214:217], v[28:29], off
	global_load_dwordx4 v[218:221], v[28:29], off offset:64
	global_load_dwordx4 v[222:225], v[28:29], off offset:512
	global_load_dwordx4 v[226:229], v[28:29], off offset:576
	global_load_dwordx4 v[230:233], v[32:33], off
	global_load_dwordx4 v[234:237], v[32:33], off offset:64
	global_load_dwordx4 v[238:241], v[32:33], off offset:512
	global_load_dwordx4 v[242:245], v[32:33], off offset:576
	s_nop 0
	v_add_co_u32_e32 v24, vcc, s19, v136
	s_waitcnt vmcnt(3)
	v_pk_fma_f32 v[14:15], v[18:19], v[216:217], v[232:233]
	v_addc_co_u32_e32 v25, vcc, 0, v137, vcc
	v_pk_fma_f32 v[12:13], v[16:17], v[214:215], v[230:231]
	global_store_dwordx4 v[24:25], v[12:15], off
	s_nop 0
	s_and_b64 vcc, exec, s[10:11]
	s_waitcnt vmcnt(3)
	v_pk_fma_f32 v[10:11], v[10:11], v[220:221], v[236:237]
	v_pk_fma_f32 v[8:9], v[8:9], v[218:219], v[234:235]
	global_store_dwordx4 v[30:31], v[8:11], off offset:64
	s_nop 0
	s_waitcnt vmcnt(3)
	v_pk_fma_f32 v[6:7], v[6:7], v[224:225], v[240:241]
	v_pk_fma_f32 v[4:5], v[4:5], v[222:223], v[238:239]
	global_store_dwordx4 v[30:31], v[4:7], off offset:512
	s_nop 0
	s_waitcnt vmcnt(3)
	v_pk_fma_f32 v[2:3], v[2:3], v[228:229], v[244:245]
	v_pk_fma_f32 v[0:1], v[0:1], v[226:227], v[242:243]
	global_store_dwordx4 v[30:31], v[0:3], off offset:576
	s_cbranch_vccz .LBB0_2626
; #define PG8_WAIT_V(n) asm volatile("s_waitcnt vmcnt(" #n ")" ::: "memory")
; #define PG8_BAR __builtin_amdgcn_s_barrier()
; template <class Epi, class Sched>
; __device__ __forceinline__ void gemm_phase(LAS unsigned char* lds, const Gemm g, const Sched& S, const Epi& E) {
;     ...
;     if (!has_next) break;
; #pragma unroll
;     for (int a = 0; a < 2; ++a)
; #pragma unroll
;       for (int b = 0; b < 2; ++b)
; #pragma unroll
;         for (int m = 0; m < 4; ++m)
; #pragma unroll
;           for (int n = 0; n < 2; ++n) acc[a][b][m][n] = (f32x4){0.f, 0.f, 0.f, 0.f};
;     cur = nxt; cA = nA; cB = nB; ++ui;
;   }
;   PG8_WAIT_V(0);
;   if (wr == 0) PG8_BAR;
;   PG8_BAR;
	s_waitcnt vmcnt(0)
	v_readlane_b32 s82, v255, 17
	v_readlane_b32 s68, v255, 20
	s_cmpk_gt_u32 s24, 0xff
	v_readlane_b32 s83, v255, 18
	s_mov_b32 s74, 0x8000
	s_mov_b32 s75, 0x10000
	s_movk_i32 s79, 0x40ff
	s_movk_i32 s78, 0x2000
	v_readlane_b32 s69, v255, 21
	v_readlane_b32 s59, v255, 19
	s_cbranch_scc1 .LBB0_2637
	s_barrier

; #define PG8_STAGE(bufoff, gbase, voff) do { _Pragma("unroll") for (int _i = 0; _i < 2; ++_i) \
;     __builtin_amdgcn_global_load_lds((const unsigned*)((const char*)(gbase) + (voff)[_i]), (LAS unsigned*)(lds + (bufoff) + ldsw + _i * 8192), 16, 0, 0); } while (0)
; #define PG8_LDA(dst, b, h) do { _Pragma("unroll") for (int m = 0; m < 4; ++m) _Pragma("unroll") for (int k = 0; k < 2; ++k) dst[m][k] = *(const LAS bf16x8*)(lds + PG8_SA(b, h) + aoff + m * 2048 + k * 1024); } while (0)
; #define PG8_LDB(dst, b, h) do { _Pragma("unroll") for (int n = 0; n < 2; ++n) _Pragma("unroll") for (int k = 0; k < 2; ++k) dst[n][k] = *(const LAS bf16x8*)(lds + PG8_SB(b, h) + boff + n * 2048 + k * 1024); } while (0)
; #define PG8_BAR __builtin_amdgcn_s_barrier()
; template <class Epi, class Sched>
; __device__ __forceinline__ void gemm_phase(LAS unsigned char* lds, const Gemm g, const Sched& S, const Epi& E) {
;     ...
;     for (int t = 0; t < nt; t += 2) {
;       const bool last = (t == nt - 2);
;       const char* a1 = cA + (size_t)(t + 1) * kstep;
;       const char* a2 = last ? nA : cA + (size_t)(t + 2) * kstep; const char* b2 = last ? nB : cB + (size_t)(t + 2) * kstep;
;       const char* a3 = a2 + kstep; const char* b3 = b2 + kstep;
;       PG8_LDB(B0, 0, 0); PG8_SCHED; PG8_LDA(At, 0, 0); PG8_STAGE(PG8_SA(1, 1), a1 + hstepA, voffA);
;       PG8_WAIT_L(8); PG8_BAR; PG8_WAIT_L(0); PG8_MMA(0, 0, At, B0); PG8_BAR; PG8_SCHED;
;       PG8_LDB(B1, 0, 1); PG8_STAGE(PG8_SB(0, 0), b2, voffB);
;       PG8_BAR; PG8_WAIT_L(0); PG8_MMA(0, 1, At, B1); PG8_BAR;
;       PG8_LDA(At, 0, 1); PG8_STAGE(PG8_SA(0, 0), a2, voffA);
;       PG8_BAR; PG8_WAIT_L(0); PG8_MMA(1, 0, At, B0); PG8_BAR; PG8_SCHED;
;       PG8_STAGE(PG8_SB(0, 1), b2 + hstepB, voffB);
;       PG8_WAIT_V(6); PG8_BAR; PG8_MMA(1, 1, At, B1); PG8_BAR;
;       PG8_LDB(B0, 1, 0); PG8_SCHED; PG8_LDA(At, 1, 0); PG8_STAGE(PG8_SA(0, 1), a2 + hstepA, voffA);
;       PG8_WAIT_L(8); PG8_BAR; PG8_WAIT_L(0); PG8_MMA(0, 0, At, B0); PG8_BAR; PG8_SCHED;
;       PG8_LDB(B1, 1, 1); PG8_STAGE(PG8_SB(1, 0), b3, voffB);
;       PG8_BAR; PG8_WAIT_L(0); PG8_MMA(0, 1, At, B1); PG8_BAR;
;       PG8_LDA(At, 1, 1); PG8_STAGE(PG8_SA(1, 0), a3, voffA);
;       PG8_BAR; PG8_WAIT_L(0); PG8_MMA(1, 0, At, B0); PG8_BAR; PG8_SCHED;
;       PG8_STAGE(PG8_SB(1, 1), b3 + hstepB, voffB);
;       PG8_WAIT_V(6); PG8_BAR; PG8_MMA(1, 1, At, B1); PG8_BAR;
.LBB0_2859:
	s_add_u32 s10, s8, 0xfff00080
	s_addc_u32 s11, s9, -1
	s_add_i32 s78, 16, 0x10000
	v_add_u32_e32 v153, s78, v150
	ds_read_b128 v[136:139], v153
	ds_read_b128 v[140:143], v153 offset:1024
	ds_read_b128 v[146:149], v153 offset:2048
	ds_read_b128 v[154:157], v153 offset:3072
	s_cmp_eq_u32 s77, 60
	s_cselect_b32 s37, s23, s11
	s_cselect_b32 s36, s69, s10
	s_cselect_b32 s11, s21, s76
	s_cselect_b32 s10, s74, s75
	v_lshl_add_u64 v[214:215], s[8:9], 0, v[132:133]
	s_add_i32 m0, s45, 0xc000
	ds_read_b128 v[158:161], v152
	ds_read_b128 v[162:165], v152 offset:1024
	ds_read_b128 v[166:169], v152 offset:2048
	ds_read_b128 v[170:173], v152 offset:3072
	ds_read_b128 v[174:177], v152 offset:4096
	ds_read_b128 v[178:181], v152 offset:5120
	ds_read_b128 v[182:185], v152 offset:6144
	ds_read_b128 v[198:201], v152 offset:7168
	global_load_lds_dwordx4 v[214:215], off
	v_lshl_add_u64 v[214:215], s[8:9], 0, v[134:135]
	s_add_i32 m0, s45, 0xe000
	s_nop 0
	global_load_lds_dwordx4 v[214:215], off
	s_waitcnt lgkmcnt(8)
	s_barrier
	s_waitcnt lgkmcnt(0)
	s_setprio 1
	s_waitcnt lgkmcnt(0)
	v_mfma_f32_16x16x32_bf16 v[124:127], v[136:139], v[158:161], v[124:127]
	v_mfma_f32_16x16x32_bf16 v[120:123], v[146:149], v[158:161], v[120:123]
	v_mfma_f32_16x16x32_bf16 v[108:111], v[136:139], v[166:169], v[108:111]
	v_mfma_f32_16x16x32_bf16 v[104:107], v[146:149], v[166:169], v[104:107]
	v_mfma_f32_16x16x32_bf16 v[92:95], v[136:139], v[174:177], v[92:95]
	v_mfma_f32_16x16x32_bf16 v[88:91], v[146:149], v[174:177], v[88:91]
	v_mfma_f32_16x16x32_bf16 v[76:79], v[136:139], v[182:185], v[76:79]
	v_mfma_f32_16x16x32_bf16 v[72:75], v[146:149], v[182:185], v[72:75]
	v_mfma_f32_16x16x32_bf16 v[124:127], v[140:143], v[162:165], v[124:127]
	v_mfma_f32_16x16x32_bf16 v[120:123], v[154:157], v[162:165], v[120:123]
	v_mfma_f32_16x16x32_bf16 v[108:111], v[140:143], v[170:173], v[108:111]
	v_mfma_f32_16x16x32_bf16 v[104:107], v[154:157], v[170:173], v[104:107]
	v_mfma_f32_16x16x32_bf16 v[92:95], v[140:143], v[178:181], v[92:95]
	v_mfma_f32_16x16x32_bf16 v[88:91], v[154:157], v[178:181], v[88:91]
	v_mfma_f32_16x16x32_bf16 v[76:79], v[140:143], v[198:201], v[76:79]
	v_mfma_f32_16x16x32_bf16 v[72:75], v[154:157], v[198:201], v[72:75]
	s_setprio 0
	s_barrier
	s_add_i32 s82, 16, 0x14000
	s_add_i32 s78, s78, s38
	v_add_u32_e32 v153, s82, v150
	v_lshl_add_u64 v[230:231], s[10:11], 0, v[130:131]
	s_mov_b32 m0, s78
	ds_read_b128 v[214:217], v153
	ds_read_b128 v[218:221], v153 offset:1024
	ds_read_b128 v[222:225], v153 offset:2048
	ds_read_b128 v[226:229], v153 offset:3072
	global_load_lds_dwordx4 v[230:231], off
	v_lshl_add_u64 v[232:233], s[10:11], 0, v[128:129]
	s_add_i32 m0, s78, 0x2000
	s_nop 0
	global_load_lds_dwordx4 v[232:233], off
	s_barrier
	s_waitcnt lgkmcnt(0)
	s_setprio 1
	s_waitcnt lgkmcnt(0)
	v_mfma_f32_16x16x32_bf16 v[116:119], v[214:217], v[158:161], v[116:119]
	v_mfma_f32_16x16x32_bf16 v[112:115], v[222:225], v[158:161], v[112:115]
	v_mfma_f32_16x16x32_bf16 v[100:103], v[214:217], v[166:169], v[100:103]
	v_mfma_f32_16x16x32_bf16 v[96:99], v[222:225], v[166:169], v[96:99]
	v_mfma_f32_16x16x32_bf16 v[84:87], v[214:217], v[174:177], v[84:87]
	v_mfma_f32_16x16x32_bf16 v[80:83], v[222:225], v[174:177], v[80:83]
	v_mfma_f32_16x16x32_bf16 v[68:71], v[214:217], v[182:185], v[68:71]
	v_mfma_f32_16x16x32_bf16 v[64:67], v[222:225], v[182:185], v[64:67]
	v_mfma_f32_16x16x32_bf16 v[116:119], v[218:221], v[162:165], v[116:119]
	v_mfma_f32_16x16x32_bf16 v[112:115], v[226:229], v[162:165], v[112:115]
	v_mfma_f32_16x16x32_bf16 v[100:103], v[218:221], v[170:173], v[100:103]
	v_mfma_f32_16x16x32_bf16 v[96:99], v[226:229], v[170:173], v[96:99]
	v_mfma_f32_16x16x32_bf16 v[84:87], v[218:221], v[178:181], v[84:87]
	v_mfma_f32_16x16x32_bf16 v[80:83], v[226:229], v[178:181], v[80:83]
	v_mfma_f32_16x16x32_bf16 v[68:71], v[218:221], v[198:201], v[68:71]
	v_mfma_f32_16x16x32_bf16 v[64:67], v[226:229], v[198:201], v[64:67]
	s_setprio 0
	s_mov_b32 m0, s45
	v_lshl_add_u64 v[234:235], s[36:37], 0, v[130:131]
	s_barrier
	ds_read_b128 v[158:161], v152 offset:16384
	ds_read_b128 v[162:165], v152 offset:17408
	ds_read_b128 v[166:169], v152 offset:18432
	ds_read_b128 v[170:173], v152 offset:19456
	ds_read_b128 v[174:177], v152 offset:20480
	ds_read_b128 v[178:181], v152 offset:21504
	ds_read_b128 v[182:185], v152 offset:22528
	ds_read_b128 v[198:201], v152 offset:23552
	global_load_lds_dwordx4 v[234:235], off
	v_lshl_add_u64 v[236:237], s[36:37], 0, v[128:129]
	s_mov_b32 m0, s46
	s_nop 0
	global_load_lds_dwordx4 v[236:237], off
	s_barrier
	s_waitcnt lgkmcnt(0)
	s_setprio 1
	s_waitcnt lgkmcnt(0)
	v_mfma_f32_16x16x32_bf16 v[60:63], v[136:139], v[158:161], v[60:63]
	v_mfma_f32_16x16x32_bf16 v[56:59], v[146:149], v[158:161], v[56:59]
	v_mfma_f32_16x16x32_bf16 v[44:47], v[136:139], v[166:169], v[44:47]
	v_mfma_f32_16x16x32_bf16 v[40:43], v[146:149], v[166:169], v[40:43]
	v_mfma_f32_16x16x32_bf16 v[28:31], v[136:139], v[174:177], v[28:31]
	v_mfma_f32_16x16x32_bf16 v[24:27], v[146:149], v[174:177], v[24:27]
	v_mfma_f32_16x16x32_bf16 v[12:15], v[136:139], v[182:185], v[12:15]
	v_mfma_f32_16x16x32_bf16 v[8:11], v[146:149], v[182:185], v[8:11]
	v_mfma_f32_16x16x32_bf16 v[60:63], v[140:143], v[162:165], v[60:63]
	v_mfma_f32_16x16x32_bf16 v[56:59], v[154:157], v[162:165], v[56:59]
	v_mfma_f32_16x16x32_bf16 v[44:47], v[140:143], v[170:173], v[44:47]
	v_mfma_f32_16x16x32_bf16 v[40:43], v[154:157], v[170:173], v[40:43]
	v_mfma_f32_16x16x32_bf16 v[28:31], v[140:143], v[178:181], v[28:31]
	v_mfma_f32_16x16x32_bf16 v[24:27], v[154:157], v[178:181], v[24:27]
	v_mfma_f32_16x16x32_bf16 v[12:15], v[140:143], v[198:201], v[12:15]
	v_mfma_f32_16x16x32_bf16 v[8:11], v[154:157], v[198:201], v[8:11]
	s_setprio 0
	s_barrier
; #define PG8_STAGE(bufoff, gbase, voff) do { _Pragma("unroll") for (int _i = 0; _i < 2; ++_i) \
;     __builtin_amdgcn_global_load_lds((const unsigned*)((const char*)(gbase) + (voff)[_i]), (LAS unsigned*)(lds + (bufoff) + ldsw + _i * 8192), 16, 0, 0); } while (0)
; #define PG8_LDA(dst, b, h) do { _Pragma("unroll") for (int m = 0; m < 4; ++m) _Pragma("unroll") for (int k = 0; k < 2; ++k) dst[m][k] = *(const LAS bf16x8*)(lds + PG8_SA(b, h) + aoff + m * 2048 + k * 1024); } while (0)
; #define PG8_LDB(dst, b, h) do { _Pragma("unroll") for (int n = 0; n < 2; ++n) _Pragma("unroll") for (int k = 0; k < 2; ++k) dst[n][k] = *(const LAS bf16x8*)(lds + PG8_SB(b, h) + boff + n * 2048 + k * 1024); } while (0)
; #define PG8_MMA(ai, bj, At, Bt) do { __builtin_amdgcn_s_setprio(1); _Pragma("unroll") for (int m = 0; m < 4; ++m) _Pragma("unroll") for (int n = 0; n < 2; ++n) _Pragma("unroll") for (int k = 0; k < 2; ++k) \
;     acc[ai][bj][m][n] = __builtin_amdgcn_mfma_f32_16x16x32_bf16(Bt[n][k], At[m][k], acc[ai][bj][m][n], 0, 0, 0); __builtin_amdgcn_s_setprio(0); } while (0)
; #define PG8_WAIT_V(n) asm volatile("s_waitcnt vmcnt(" #n ")" ::: "memory")
; #define PG8_WAIT_L(n) asm volatile("s_waitcnt lgkmcnt(" #n ")" ::: "memory")
; #define PG8_BAR __builtin_amdgcn_s_barrier()
; #define PG8_SCHED __builtin_amdgcn_sched_barrier(0)
; template <class Epi, class Sched>
; __device__ __forceinline__ void gemm_phase(LAS unsigned char* lds, const Gemm g, const Sched& S, const Epi& E) {
;     ...
;       PG8_LDA(At, 0, 1); PG8_STAGE(PG8_SA(0, 0), a2, voffA);
;       PG8_BAR; PG8_WAIT_L(0); PG8_MMA(1, 0, At, B0); PG8_BAR; PG8_SCHED;
;       PG8_STAGE(PG8_SB(0, 1), b2 + hstepB, voffB);
;       PG8_WAIT_V(6); PG8_BAR; PG8_MMA(1, 1, At, B1); PG8_BAR;
;       PG8_LDB(B0, 1, 0); PG8_SCHED; PG8_LDA(At, 1, 0); PG8_STAGE(PG8_SA(0, 1), a2 + hstepA, voffA);
;       PG8_WAIT_L(8); PG8_BAR; PG8_WAIT_L(0); PG8_MMA(0, 0, At, B0); PG8_BAR; PG8_SCHED;
;       PG8_LDB(B1, 1, 1); PG8_STAGE(PG8_SB(1, 0), b3, voffB);
;       PG8_BAR; PG8_WAIT_L(0); PG8_MMA(0, 1, At, B1); PG8_BAR;
;       PG8_LDA(At, 1, 1); PG8_STAGE(PG8_SA(1, 0), a3, voffA);
;       PG8_BAR; PG8_WAIT_L(0); PG8_MMA(1, 0, At, B0); PG8_BAR; PG8_SCHED;
	s_add_u32 s78, s10, 0x100000
	s_addc_u32 s79, s11, 0
	s_add_i32 s82, s82, s38
	v_lshl_add_u64 v[136:137], s[78:79], 0, v[130:131]
	s_mov_b32 m0, s82
	s_nop 0
	global_load_lds_dwordx4 v[136:137], off
	v_lshl_add_u64 v[136:137], s[78:79], 0, v[128:129]
	s_add_i32 m0, s82, 0x2000
	s_nop 0
	global_load_lds_dwordx4 v[136:137], off
	s_waitcnt vmcnt(6)
	s_barrier
	s_setprio 1
	v_mfma_f32_16x16x32_bf16 v[52:55], v[214:217], v[158:161], v[52:55]
	v_mfma_f32_16x16x32_bf16 v[48:51], v[222:225], v[158:161], v[48:51]
	v_mfma_f32_16x16x32_bf16 v[36:39], v[214:217], v[166:169], v[36:39]
	v_mfma_f32_16x16x32_bf16 v[32:35], v[222:225], v[166:169], v[32:35]
	v_mfma_f32_16x16x32_bf16 v[20:23], v[214:217], v[174:177], v[20:23]
	v_mfma_f32_16x16x32_bf16 v[16:19], v[222:225], v[174:177], v[16:19]
	v_mfma_f32_16x16x32_bf16 v[4:7], v[214:217], v[182:185], v[4:7]
	v_mfma_f32_16x16x32_bf16 v[0:3], v[222:225], v[182:185], v[0:3]
	v_mfma_f32_16x16x32_bf16 v[52:55], v[218:221], v[162:165], v[52:55]
	v_mfma_f32_16x16x32_bf16 v[48:51], v[226:229], v[162:165], v[48:51]
	v_mfma_f32_16x16x32_bf16 v[36:39], v[218:221], v[170:173], v[36:39]
	v_mfma_f32_16x16x32_bf16 v[32:35], v[226:229], v[170:173], v[32:35]
	v_mfma_f32_16x16x32_bf16 v[20:23], v[218:221], v[178:181], v[20:23]
	v_mfma_f32_16x16x32_bf16 v[16:19], v[226:229], v[178:181], v[16:19]
	v_mfma_f32_16x16x32_bf16 v[4:7], v[218:221], v[198:201], v[4:7]
	v_mfma_f32_16x16x32_bf16 v[0:3], v[226:229], v[198:201], v[0:3]
	s_setprio 0
	s_add_i32 s78, 16, 0x18000
	v_add_u32_e32 v153, s78, v150
	s_barrier
	ds_read_b128 v[136:139], v153
	ds_read_b128 v[140:143], v153 offset:1024
	ds_read_b128 v[146:149], v153 offset:2048
	ds_read_b128 v[154:157], v153 offset:3072
	s_add_u32 s36, s36, 0x100000
	s_addc_u32 s37, s37, 0
	s_mov_b32 m0, s47
	v_lshl_add_u64 v[214:215], s[36:37], 0, v[130:131]
	ds_read_b128 v[158:161], v152 offset:32768
	ds_read_b128 v[162:165], v152 offset:33792
	ds_read_b128 v[166:169], v152 offset:34816
	ds_read_b128 v[170:173], v152 offset:35840
	ds_read_b128 v[174:177], v152 offset:36864
	ds_read_b128 v[178:181], v152 offset:37888
	ds_read_b128 v[182:185], v152 offset:38912
	ds_read_b128 v[198:201], v152 offset:39936
	global_load_lds_dwordx4 v[214:215], off
	v_lshl_add_u64 v[214:215], s[36:37], 0, v[128:129]
	s_mov_b32 m0, s48
	s_nop 0
	global_load_lds_dwordx4 v[214:215], off
	s_waitcnt lgkmcnt(8)
	s_barrier
	s_waitcnt lgkmcnt(0)
	s_setprio 1
	s_waitcnt lgkmcnt(0)
	v_mfma_f32_16x16x32_bf16 v[124:127], v[136:139], v[158:161], v[124:127]
	v_mfma_f32_16x16x32_bf16 v[120:123], v[146:149], v[158:161], v[120:123]
	v_mfma_f32_16x16x32_bf16 v[108:111], v[136:139], v[166:169], v[108:111]
	v_mfma_f32_16x16x32_bf16 v[104:107], v[146:149], v[166:169], v[104:107]
	v_mfma_f32_16x16x32_bf16 v[92:95], v[136:139], v[174:177], v[92:95]
	v_mfma_f32_16x16x32_bf16 v[88:91], v[146:149], v[174:177], v[88:91]
	v_mfma_f32_16x16x32_bf16 v[76:79], v[136:139], v[182:185], v[76:79]
	v_mfma_f32_16x16x32_bf16 v[72:75], v[146:149], v[182:185], v[72:75]
	v_mfma_f32_16x16x32_bf16 v[124:127], v[140:143], v[162:165], v[124:127]
	v_mfma_f32_16x16x32_bf16 v[120:123], v[154:157], v[162:165], v[120:123]
	v_mfma_f32_16x16x32_bf16 v[108:111], v[140:143], v[170:173], v[108:111]
	v_mfma_f32_16x16x32_bf16 v[104:107], v[154:157], v[170:173], v[104:107]
	v_mfma_f32_16x16x32_bf16 v[92:95], v[140:143], v[178:181], v[92:95]
	v_mfma_f32_16x16x32_bf16 v[88:91], v[154:157], v[178:181], v[88:91]
	v_mfma_f32_16x16x32_bf16 v[76:79], v[140:143], v[198:201], v[76:79]
	v_mfma_f32_16x16x32_bf16 v[72:75], v[154:157], v[198:201], v[72:75]
	s_setprio 0
	s_barrier
	s_add_i32 s36, 16, 0x1c000
	s_add_i32 s37, s78, s38
	v_add_u32_e32 v153, s36, v150
	v_lshl_add_u64 v[230:231], v[230:231], 0, s[62:63]
	s_mov_b32 m0, s37
	ds_read_b128 v[214:217], v153
	ds_read_b128 v[218:221], v153 offset:1024
	ds_read_b128 v[222:225], v153 offset:2048
	ds_read_b128 v[226:229], v153 offset:3072
	global_load_lds_dwordx4 v[230:231], off
	v_lshl_add_u64 v[230:231], v[232:233], 0, s[62:63]
	s_add_i32 m0, s37, 0x2000
	s_nop 0
	global_load_lds_dwordx4 v[230:231], off
	s_barrier
	s_waitcnt lgkmcnt(0)
	s_setprio 1
	s_waitcnt lgkmcnt(0)
	v_mfma_f32_16x16x32_bf16 v[116:119], v[214:217], v[158:161], v[116:119]
	v_mfma_f32_16x16x32_bf16 v[112:115], v[222:225], v[158:161], v[112:115]
	v_mfma_f32_16x16x32_bf16 v[100:103], v[214:217], v[166:169], v[100:103]
	v_mfma_f32_16x16x32_bf16 v[96:99], v[222:225], v[166:169], v[96:99]
	v_mfma_f32_16x16x32_bf16 v[84:87], v[214:217], v[174:177], v[84:87]
	v_mfma_f32_16x16x32_bf16 v[80:83], v[222:225], v[174:177], v[80:83]
	v_mfma_f32_16x16x32_bf16 v[68:71], v[214:217], v[182:185], v[68:71]
	v_mfma_f32_16x16x32_bf16 v[64:67], v[222:225], v[182:185], v[64:67]
	v_mfma_f32_16x16x32_bf16 v[116:119], v[218:221], v[162:165], v[116:119]
	v_mfma_f32_16x16x32_bf16 v[112:115], v[226:229], v[162:165], v[112:115]
	v_mfma_f32_16x16x32_bf16 v[100:103], v[218:221], v[170:173], v[100:103]
	v_mfma_f32_16x16x32_bf16 v[96:99], v[226:229], v[170:173], v[96:99]
	v_mfma_f32_16x16x32_bf16 v[84:87], v[218:221], v[178:181], v[84:87]
	v_mfma_f32_16x16x32_bf16 v[80:83], v[226:229], v[178:181], v[80:83]
	v_mfma_f32_16x16x32_bf16 v[68:71], v[218:221], v[198:201], v[68:71]
	v_mfma_f32_16x16x32_bf16 v[64:67], v[226:229], v[198:201], v[64:67]
	s_setprio 0
	s_mov_b32 m0, s66
	v_lshl_add_u64 v[230:231], v[234:235], 0, s[62:63]
	s_barrier
; #define PG8_STAGE(bufoff, gbase, voff) do { _Pragma("unroll") for (int _i = 0; _i < 2; ++_i) \
;     __builtin_amdgcn_global_load_lds((const unsigned*)((const char*)(gbase) + (voff)[_i]), (LAS unsigned*)(lds + (bufoff) + ldsw + _i * 8192), 16, 0, 0); } while (0)
; #define PG8_LDA(dst, b, h) do { _Pragma("unroll") for (int m = 0; m < 4; ++m) _Pragma("unroll") for (int k = 0; k < 2; ++k) dst[m][k] = *(const LAS bf16x8*)(lds + PG8_SA(b, h) + aoff + m * 2048 + k * 1024); } while (0)
; #define PG8_LDB(dst, b, h) do { _Pragma("unroll") for (int n = 0; n < 2; ++n) _Pragma("unroll") for (int k = 0; k < 2; ++k) dst[n][k] = *(const LAS bf16x8*)(lds + PG8_SB(b, h) + boff + n * 2048 + k * 1024); } while (0)
; #define PG8_MMA(ai, bj, At, Bt) do { __builtin_amdgcn_s_setprio(1); _Pragma("unroll") for (int m = 0; m < 4; ++m) _Pragma("unroll") for (int n = 0; n < 2; ++n) _Pragma("unroll") for (int k = 0; k < 2; ++k) \
;     acc[ai][bj][m][n] = __builtin_amdgcn_mfma_f32_16x16x32_bf16(Bt[n][k], At[m][k], acc[ai][bj][m][n], 0, 0, 0); __builtin_amdgcn_s_setprio(0); } while (0)
; #define PG8_WAIT_V(n) asm volatile("s_waitcnt vmcnt(" #n ")" ::: "memory")
; #define PG8_WAIT_L(n) asm volatile("s_waitcnt lgkmcnt(" #n ")" ::: "memory")
; #define PG8_BAR __builtin_amdgcn_s_barrier()
; #define PG8_SCHED __builtin_amdgcn_sched_barrier(0)
; template <class Epi, class Sched>
; __device__ __forceinline__ void gemm_phase(LAS unsigned char* lds, const Gemm g, const Sched& S, const Epi& E) {
;     ...
;       PG8_WAIT_V(6); PG8_BAR; PG8_MMA(1, 1, At, B1); PG8_BAR;
;       PG8_LDB(B0, 1, 0); PG8_SCHED; PG8_LDA(At, 1, 0); PG8_STAGE(PG8_SA(0, 1), a2 + hstepA, voffA);
;       PG8_WAIT_L(8); PG8_BAR; PG8_WAIT_L(0); PG8_MMA(0, 0, At, B0); PG8_BAR; PG8_SCHED;
;       PG8_LDB(B1, 1, 1); PG8_STAGE(PG8_SB(1, 0), b3, voffB);
;       PG8_BAR; PG8_WAIT_L(0); PG8_MMA(0, 1, At, B1); PG8_BAR;
;       PG8_LDA(At, 1, 1); PG8_STAGE(PG8_SA(1, 0), a3, voffA);
;       PG8_BAR; PG8_WAIT_L(0); PG8_MMA(1, 0, At, B0); PG8_BAR; PG8_SCHED;
;       PG8_STAGE(PG8_SB(1, 1), b3 + hstepB, voffB);
;       PG8_WAIT_V(6); PG8_BAR; PG8_MMA(1, 1, At, B1); PG8_BAR;
	ds_read_b128 v[158:161], v152 offset:49152
	ds_read_b128 v[162:165], v152 offset:50176
	ds_read_b128 v[166:169], v152 offset:51200
	ds_read_b128 v[170:173], v152 offset:52224
	ds_read_b128 v[174:177], v152 offset:53248
	ds_read_b128 v[178:181], v152 offset:54272
	ds_read_b128 v[182:185], v152 offset:55296
	ds_read_b128 v[198:201], v152 offset:56320
	global_load_lds_dwordx4 v[230:231], off
	v_lshl_add_u64 v[230:231], v[236:237], 0, s[62:63]
	s_mov_b32 m0, s67
	s_nop 0
	global_load_lds_dwordx4 v[230:231], off
	s_barrier
	s_waitcnt lgkmcnt(0)
	s_setprio 1
	s_waitcnt lgkmcnt(0)
	v_mfma_f32_16x16x32_bf16 v[60:63], v[136:139], v[158:161], v[60:63]
	v_mfma_f32_16x16x32_bf16 v[56:59], v[146:149], v[158:161], v[56:59]
	v_mfma_f32_16x16x32_bf16 v[44:47], v[136:139], v[166:169], v[44:47]
	v_mfma_f32_16x16x32_bf16 v[40:43], v[146:149], v[166:169], v[40:43]
	v_mfma_f32_16x16x32_bf16 v[28:31], v[136:139], v[174:177], v[28:31]
	v_mfma_f32_16x16x32_bf16 v[24:27], v[146:149], v[174:177], v[24:27]
	v_mfma_f32_16x16x32_bf16 v[12:15], v[136:139], v[182:185], v[12:15]
	v_mfma_f32_16x16x32_bf16 v[8:11], v[146:149], v[182:185], v[8:11]
	v_mfma_f32_16x16x32_bf16 v[60:63], v[140:143], v[162:165], v[60:63]
	v_mfma_f32_16x16x32_bf16 v[56:59], v[154:157], v[162:165], v[56:59]
	v_mfma_f32_16x16x32_bf16 v[44:47], v[140:143], v[170:173], v[44:47]
	v_mfma_f32_16x16x32_bf16 v[40:43], v[154:157], v[170:173], v[40:43]
	v_mfma_f32_16x16x32_bf16 v[28:31], v[140:143], v[178:181], v[28:31]
	v_mfma_f32_16x16x32_bf16 v[24:27], v[154:157], v[178:181], v[24:27]
	v_mfma_f32_16x16x32_bf16 v[12:15], v[140:143], v[198:201], v[12:15]
	v_mfma_f32_16x16x32_bf16 v[8:11], v[154:157], v[198:201], v[8:11]
	s_setprio 0
	s_barrier
	s_add_u32 s10, s10, 0x100080
	s_addc_u32 s11, s11, 0
	s_add_i32 s36, s36, s38
	v_lshl_add_u64 v[136:137], s[10:11], 0, v[130:131]
	s_mov_b32 m0, s36
	s_nop 0
	global_load_lds_dwordx4 v[136:137], off
	v_lshl_add_u64 v[136:137], s[10:11], 0, v[128:129]
	s_add_i32 m0, s36, 0x2000
	s_nop 0
	global_load_lds_dwordx4 v[136:137], off
	s_waitcnt vmcnt(6)
	s_barrier
	s_setprio 1
	v_mfma_f32_16x16x32_bf16 v[52:55], v[214:217], v[158:161], v[52:55]
	v_mfma_f32_16x16x32_bf16 v[48:51], v[222:225], v[158:161], v[48:51]
	v_mfma_f32_16x16x32_bf16 v[36:39], v[214:217], v[166:169], v[36:39]
	v_mfma_f32_16x16x32_bf16 v[32:35], v[222:225], v[166:169], v[32:35]
	v_mfma_f32_16x16x32_bf16 v[20:23], v[214:217], v[174:177], v[20:23]
	v_mfma_f32_16x16x32_bf16 v[16:19], v[222:225], v[174:177], v[16:19]
	v_mfma_f32_16x16x32_bf16 v[4:7], v[214:217], v[182:185], v[4:7]
	v_mfma_f32_16x16x32_bf16 v[0:3], v[222:225], v[182:185], v[0:3]
	v_mfma_f32_16x16x32_bf16 v[52:55], v[218:221], v[162:165], v[52:55]
	v_mfma_f32_16x16x32_bf16 v[48:51], v[226:229], v[162:165], v[48:51]
	v_mfma_f32_16x16x32_bf16 v[36:39], v[218:221], v[170:173], v[36:39]
	v_mfma_f32_16x16x32_bf16 v[32:35], v[226:229], v[170:173], v[32:35]
	v_mfma_f32_16x16x32_bf16 v[20:23], v[218:221], v[178:181], v[20:23]
	v_mfma_f32_16x16x32_bf16 v[16:19], v[226:229], v[178:181], v[16:19]
	v_mfma_f32_16x16x32_bf16 v[4:7], v[218:221], v[198:201], v[4:7]
	v_mfma_f32_16x16x32_bf16 v[0:3], v[226:229], v[198:201], v[0:3]
	s_setprio 0
	s_add_i32 s77, s77, 2
	s_add_u32 s8, s8, 0x100
	s_addc_u32 s9, s9, 0
	s_add_u32 s75, s75, 0x100
	s_addc_u32 s76, s76, 0
	s_cmp_gt_u32 s77, 61
	s_barrier
	s_cbranch_scc0 .LBB0_2859
	v_lshl_add_u32 v138, s25, 8, v145
	v_mov_b32_e32 v137, s51
	v_mov_b32_e32 v140, s59
	v_cmp_gt_i32_e32 vcc, s73, v138
	v_lshl_or_b32 v136, s24, 8, v151
	v_ashrrev_i32_e32 v139, 31, v138
	v_cndmask_b32_e32 v147, v137, v140, vcc
	v_mov_b32_e32 v137, s49
	v_mov_b32_e32 v140, s58
	v_lshlrev_b64 v[142:143], 12, v[138:139]
	v_cndmask_b32_e32 v146, v137, v140, vcc
	v_ashrrev_i32_e32 v137, 31, v136
	v_lshlrev_b64 v[140:141], 2, v[136:137]
	v_lshl_add_u64 v[142:143], s[14:15], 0, v[142:143]
	v_lshl_add_u64 v[148:149], v[146:147], 0, v[140:141]
	v_lshl_add_u64 v[142:143], v[142:143], 0, v[140:141]
	global_load_dwordx4 v[214:217], v[148:149], off
	global_load_dwordx4 v[218:221], v[148:149], off offset:64
	global_load_dwordx4 v[222:225], v[148:149], off offset:512
	global_load_dwordx4 v[226:229], v[148:149], off offset:576
	global_load_dwordx4 v[230:233], v[142:143], off
	global_load_dwordx4 v[234:237], v[142:143], off offset:64
	global_load_dwordx4 v[238:241], v[142:143], off offset:512
	global_load_dwordx4 v[242:245], v[142:143], off offset:576
	v_mov_b32_e32 v147, v144
	v_cndmask_b32_e64 v153, 0, 1, s[18:19]
	v_add_u32_e32 v146, 0xffffff00, v138
	v_cmp_lt_i32_e64 s[10:11], s81, v138
	v_cmp_ne_u32_e64 s[8:9], 1, v153
	v_lshlrev_b64 v[146:147], 12, v[146:147]
	s_andn2_b64 vcc, exec, s[18:19]
	s_waitcnt vmcnt(3)
	v_pk_fma_f32 v[126:127], v[126:127], v[216:217], v[232:233]
	v_pk_fma_f32 v[124:125], v[124:125], v[214:215], v[230:231]
	s_cbranch_vccnz .LBB0_3019
	s_and_saveexec_b64 s[24:25], s[10:11]
	s_mov_b32 s74, 0x8000
	s_mov_b32 s75, 0x10000
	s_cbranch_execz .LBB0_2863
	v_lshl_add_u64 v[154:155], s[16:17], 0, v[146:147]
	v_lshl_add_u64 v[154:155], v[136:137], 2, v[154:155]
	global_store_dwordx4 v[154:155], v[124:127], off

.LBB0_2865:
	s_nop 0
	s_and_b64 vcc, exec, s[8:9]
	s_movk_i32 s79, 0x40ff
	s_movk_i32 s78, 0x2000
	s_waitcnt vmcnt(3)
	v_pk_fma_f32 v[122:123], v[122:123], v[220:221], v[236:237]
	v_pk_fma_f32 v[120:121], v[120:121], v[218:219], v[234:235]
	s_cbranch_vccnz .LBB0_3020
	s_and_saveexec_b64 s[24:25], s[10:11]
	s_cbranch_execz .LBB0_2868
	v_lshl_add_u64 v[124:125], s[16:17], 0, v[146:147]
	v_lshl_add_u64 v[124:125], v[136:137], 2, v[124:125]
	global_store_dwordx4 v[124:125], v[120:123], off offset:64

.LBB0_2870:
	s_nop 0
	s_and_b64 vcc, exec, s[8:9]
	s_waitcnt vmcnt(3)
	v_pk_fma_f32 v[118:119], v[118:119], v[224:225], v[240:241]
	v_pk_fma_f32 v[116:117], v[116:117], v[222:223], v[238:239]
	s_cbranch_vccnz .LBB0_3021
	s_and_saveexec_b64 s[24:25], s[10:11]
	s_cbranch_execz .LBB0_2873
	v_lshl_add_u64 v[120:121], s[16:17], 0, v[146:147]
	v_lshl_add_u64 v[120:121], v[136:137], 2, v[120:121]
	global_store_dwordx4 v[120:121], v[116:119], off offset:512

.LBB0_2875:
	s_nop 0
	s_and_b64 vcc, exec, s[8:9]
	s_waitcnt vmcnt(3)
	v_pk_fma_f32 v[114:115], v[114:115], v[228:229], v[244:245]
	v_pk_fma_f32 v[112:113], v[112:113], v[226:227], v[242:243]
	s_cbranch_vccnz .LBB0_3022
	s_and_saveexec_b64 s[24:25], s[10:11]
	s_cbranch_execz .LBB0_2878
	v_lshl_add_u64 v[116:117], s[16:17], 0, v[146:147]
	v_lshl_add_u64 v[116:117], v[136:137], 2, v[116:117]
	global_store_dwordx4 v[116:117], v[112:115], off offset:576

.LBB0_2880:
	s_nop 1
	v_or_b32_e32 v114, 16, v138
	v_ashrrev_i32_e32 v115, 31, v114
	v_lshlrev_b64 v[112:113], 12, v[114:115]
	v_mov_b32_e32 v115, s51
	v_mov_b32_e32 v116, s59
	v_cmp_gt_i32_e32 vcc, s73, v114
	v_lshl_add_u64 v[112:113], s[14:15], 0, v[112:113]
	v_lshl_add_u64 v[112:113], v[112:113], 0, v[140:141]
	v_cndmask_b32_e32 v117, v115, v116, vcc
	v_mov_b32_e32 v115, s49
	v_mov_b32_e32 v116, s58
	v_cndmask_b32_e32 v116, v115, v116, vcc
	v_lshl_add_u64 v[116:117], v[116:117], 0, v[140:141]
	global_load_dwordx4 v[214:217], v[116:117], off
	global_load_dwordx4 v[218:221], v[116:117], off offset:64
	global_load_dwordx4 v[222:225], v[116:117], off offset:512
	global_load_dwordx4 v[226:229], v[116:117], off offset:576
	global_load_dwordx4 v[230:233], v[112:113], off
	global_load_dwordx4 v[234:237], v[112:113], off offset:64
	global_load_dwordx4 v[238:241], v[112:113], off offset:512
	global_load_dwordx4 v[242:245], v[112:113], off offset:576
	v_add_u32_e32 v126, 0xffffff10, v138
	v_mov_b32_e32 v127, v144
	s_and_b64 vcc, exec, s[8:9]
	v_cmp_lt_i32_e64 s[10:11], s81, v114
	v_lshlrev_b64 v[114:115], 12, v[126:127]
	s_waitcnt vmcnt(3)
	v_pk_fma_f32 v[110:111], v[110:111], v[216:217], v[232:233]
	v_pk_fma_f32 v[108:109], v[108:109], v[214:215], v[230:231]
	s_cbranch_vccnz .LBB0_3023
	s_and_saveexec_b64 s[24:25], s[10:11]
	s_cbranch_execz .LBB0_2883
	v_lshl_add_u64 v[118:119], s[16:17], 0, v[114:115]
	v_lshl_add_u64 v[118:119], v[136:137], 2, v[118:119]
	global_store_dwordx4 v[118:119], v[108:111], off

.LBB0_2885:
	s_nop 0
	s_and_b64 vcc, exec, s[8:9]
	s_waitcnt vmcnt(3)
	v_pk_fma_f32 v[106:107], v[106:107], v[220:221], v[236:237]
	v_pk_fma_f32 v[104:105], v[104:105], v[218:219], v[234:235]
	s_cbranch_vccnz .LBB0_3024
	s_and_saveexec_b64 s[24:25], s[10:11]
	s_cbranch_execz .LBB0_2888
	v_lshl_add_u64 v[108:109], s[16:17], 0, v[114:115]
	v_lshl_add_u64 v[108:109], v[136:137], 2, v[108:109]
	global_store_dwordx4 v[108:109], v[104:107], off offset:64

.LBB0_2890:
	s_nop 0
	s_and_b64 vcc, exec, s[8:9]
	s_waitcnt vmcnt(3)
	v_pk_fma_f32 v[102:103], v[102:103], v[224:225], v[240:241]
	v_pk_fma_f32 v[100:101], v[100:101], v[222:223], v[238:239]
	s_cbranch_vccnz .LBB0_3025
	s_and_saveexec_b64 s[24:25], s[10:11]
	s_cbranch_execz .LBB0_2893
	v_lshl_add_u64 v[104:105], s[16:17], 0, v[114:115]
	v_lshl_add_u64 v[104:105], v[136:137], 2, v[104:105]
	global_store_dwordx4 v[104:105], v[100:103], off offset:512

.LBB0_2895:
	s_nop 0
	s_and_b64 vcc, exec, s[8:9]
	s_waitcnt vmcnt(3)
	v_pk_fma_f32 v[98:99], v[98:99], v[228:229], v[244:245]
	v_pk_fma_f32 v[96:97], v[96:97], v[226:227], v[242:243]
	s_cbranch_vccnz .LBB0_3026
	s_and_saveexec_b64 s[24:25], s[10:11]
	s_cbranch_execz .LBB0_2898
	v_lshl_add_u64 v[100:101], s[16:17], 0, v[114:115]
	v_lshl_add_u64 v[100:101], v[136:137], 2, v[100:101]
	global_store_dwordx4 v[100:101], v[96:99], off offset:576

.LBB0_2900:
	s_nop 1
	v_or_b32_e32 v98, 32, v138
	v_ashrrev_i32_e32 v99, 31, v98
	v_lshlrev_b64 v[96:97], 12, v[98:99]
	v_mov_b32_e32 v99, s51
	v_mov_b32_e32 v100, s59
	v_cmp_gt_i32_e32 vcc, s73, v98
	v_lshl_add_u64 v[96:97], s[14:15], 0, v[96:97]
	v_lshl_add_u64 v[96:97], v[96:97], 0, v[140:141]
	v_cndmask_b32_e32 v101, v99, v100, vcc
	v_mov_b32_e32 v99, s49
	v_mov_b32_e32 v100, s58
	v_cndmask_b32_e32 v100, v99, v100, vcc
	v_lshl_add_u64 v[100:101], v[100:101], 0, v[140:141]
	global_load_dwordx4 v[214:217], v[100:101], off
	global_load_dwordx4 v[218:221], v[100:101], off offset:64
	global_load_dwordx4 v[222:225], v[100:101], off offset:512
	global_load_dwordx4 v[226:229], v[100:101], off offset:576
	global_load_dwordx4 v[230:233], v[96:97], off
	global_load_dwordx4 v[234:237], v[96:97], off offset:64
	global_load_dwordx4 v[238:241], v[96:97], off offset:512
	global_load_dwordx4 v[242:245], v[96:97], off offset:576
	v_add_u32_e32 v110, 0xffffff20, v138
	v_mov_b32_e32 v111, v144
	s_and_b64 vcc, exec, s[8:9]
	v_cmp_lt_i32_e64 s[10:11], s81, v98
	v_lshlrev_b64 v[98:99], 12, v[110:111]
	s_waitcnt vmcnt(3)
	v_pk_fma_f32 v[94:95], v[94:95], v[216:217], v[232:233]
	v_pk_fma_f32 v[92:93], v[92:93], v[214:215], v[230:231]
	s_cbranch_vccnz .LBB0_3027
	s_and_saveexec_b64 s[24:25], s[10:11]
	s_cbranch_execz .LBB0_2903
	v_lshl_add_u64 v[102:103], s[16:17], 0, v[98:99]
	v_lshl_add_u64 v[102:103], v[136:137], 2, v[102:103]
	global_store_dwordx4 v[102:103], v[92:95], off

.LBB0_2905:
	s_nop 0
	s_and_b64 vcc, exec, s[8:9]
	s_waitcnt vmcnt(3)
	v_pk_fma_f32 v[90:91], v[90:91], v[220:221], v[236:237]
	v_pk_fma_f32 v[88:89], v[88:89], v[218:219], v[234:235]
	s_cbranch_vccnz .LBB0_3028
	s_and_saveexec_b64 s[24:25], s[10:11]
	s_cbranch_execz .LBB0_2908
	v_lshl_add_u64 v[92:93], s[16:17], 0, v[98:99]
	v_lshl_add_u64 v[92:93], v[136:137], 2, v[92:93]
	global_store_dwordx4 v[92:93], v[88:91], off offset:64

.LBB0_2910:
	s_nop 0
	s_and_b64 vcc, exec, s[8:9]
	s_waitcnt vmcnt(3)
	v_pk_fma_f32 v[86:87], v[86:87], v[224:225], v[240:241]
	v_pk_fma_f32 v[84:85], v[84:85], v[222:223], v[238:239]
	s_cbranch_vccnz .LBB0_3029
	s_and_saveexec_b64 s[24:25], s[10:11]
	s_cbranch_execz .LBB0_2913
	v_lshl_add_u64 v[88:89], s[16:17], 0, v[98:99]
	v_lshl_add_u64 v[88:89], v[136:137], 2, v[88:89]
	global_store_dwordx4 v[88:89], v[84:87], off offset:512

.LBB0_2915:
	s_nop 0
	s_and_b64 vcc, exec, s[8:9]
	s_waitcnt vmcnt(3)
	v_pk_fma_f32 v[82:83], v[82:83], v[228:229], v[244:245]
	v_pk_fma_f32 v[80:81], v[80:81], v[226:227], v[242:243]
	s_cbranch_vccnz .LBB0_3030
	s_and_saveexec_b64 s[24:25], s[10:11]
	s_cbranch_execz .LBB0_2918
	v_lshl_add_u64 v[84:85], s[16:17], 0, v[98:99]
	v_lshl_add_u64 v[84:85], v[136:137], 2, v[84:85]
	global_store_dwordx4 v[84:85], v[80:83], off offset:576

.LBB0_2920:
	s_nop 1
	v_or_b32_e32 v82, 48, v138
	v_ashrrev_i32_e32 v83, 31, v82
	v_lshlrev_b64 v[80:81], 12, v[82:83]
	v_mov_b32_e32 v83, s51
	v_mov_b32_e32 v84, s59
	v_cmp_gt_i32_e32 vcc, s73, v82
	v_lshl_add_u64 v[80:81], s[14:15], 0, v[80:81]
	v_lshl_add_u64 v[80:81], v[80:81], 0, v[140:141]
	v_cndmask_b32_e32 v85, v83, v84, vcc
	v_mov_b32_e32 v83, s49
	v_mov_b32_e32 v84, s58
	v_cndmask_b32_e32 v84, v83, v84, vcc
	v_lshl_add_u64 v[84:85], v[84:85], 0, v[140:141]
	global_load_dwordx4 v[214:217], v[84:85], off
	global_load_dwordx4 v[218:221], v[84:85], off offset:64
	global_load_dwordx4 v[222:225], v[84:85], off offset:512
	global_load_dwordx4 v[226:229], v[84:85], off offset:576
	global_load_dwordx4 v[230:233], v[80:81], off
	global_load_dwordx4 v[234:237], v[80:81], off offset:64
	global_load_dwordx4 v[238:241], v[80:81], off offset:512
	global_load_dwordx4 v[242:245], v[80:81], off offset:576
	v_add_u32_e32 v94, 0xffffff30, v138
	v_mov_b32_e32 v95, v144
	s_and_b64 vcc, exec, s[8:9]
	v_cmp_lt_i32_e64 s[10:11], s81, v82
	v_lshlrev_b64 v[82:83], 12, v[94:95]
	s_waitcnt vmcnt(3)
	v_pk_fma_f32 v[78:79], v[78:79], v[216:217], v[232:233]
	v_pk_fma_f32 v[76:77], v[76:77], v[214:215], v[230:231]
	s_cbranch_vccnz .LBB0_3031
	s_and_saveexec_b64 s[24:25], s[10:11]
	s_cbranch_execz .LBB0_2923
	v_lshl_add_u64 v[86:87], s[16:17], 0, v[82:83]
	v_lshl_add_u64 v[86:87], v[136:137], 2, v[86:87]
	global_store_dwordx4 v[86:87], v[76:79], off

.LBB0_2925:
	s_nop 0
	s_and_b64 vcc, exec, s[8:9]
	s_waitcnt vmcnt(3)
	v_pk_fma_f32 v[74:75], v[74:75], v[220:221], v[236:237]
	v_pk_fma_f32 v[72:73], v[72:73], v[218:219], v[234:235]
	s_cbranch_vccnz .LBB0_3032
	s_and_saveexec_b64 s[24:25], s[10:11]
	s_cbranch_execz .LBB0_2928
	v_lshl_add_u64 v[76:77], s[16:17], 0, v[82:83]
	v_lshl_add_u64 v[76:77], v[136:137], 2, v[76:77]
	global_store_dwordx4 v[76:77], v[72:75], off offset:64

.LBB0_2930:
	s_nop 0
	s_and_b64 vcc, exec, s[8:9]
	s_waitcnt vmcnt(3)
	v_pk_fma_f32 v[70:71], v[70:71], v[224:225], v[240:241]
	v_pk_fma_f32 v[68:69], v[68:69], v[222:223], v[238:239]
	s_cbranch_vccnz .LBB0_3033
	s_and_saveexec_b64 s[24:25], s[10:11]
	s_cbranch_execz .LBB0_2933
	v_lshl_add_u64 v[72:73], s[16:17], 0, v[82:83]
	v_lshl_add_u64 v[72:73], v[136:137], 2, v[72:73]
	global_store_dwordx4 v[72:73], v[68:71], off offset:512

.LBB0_2935:
	s_nop 0
	s_and_b64 vcc, exec, s[8:9]
	s_waitcnt vmcnt(3)
	v_pk_fma_f32 v[66:67], v[66:67], v[228:229], v[244:245]
	v_pk_fma_f32 v[64:65], v[64:65], v[226:227], v[242:243]
	s_cbranch_vccnz .LBB0_3034
	s_and_saveexec_b64 s[24:25], s[10:11]
	s_cbranch_execz .LBB0_2938
	v_lshl_add_u64 v[68:69], s[16:17], 0, v[82:83]
	v_lshl_add_u64 v[68:69], v[136:137], 2, v[68:69]
	global_store_dwordx4 v[68:69], v[64:67], off offset:576

.LBB0_2940:
	s_movk_i32 s10, 0x80
	s_nop 0
	v_lshlrev_b64 v[64:65], 12, v[138:139]
	v_mov_b32_e32 v66, s51
	v_mov_b32_e32 v67, s59
	v_cmp_gt_i32_e32 vcc, s10, v138
	v_mov_b32_e32 v68, s58
	v_lshl_add_u64 v[64:65], s[14:15], 0, v[64:65]
	v_cndmask_b32_e32 v67, v66, v67, vcc
	v_mov_b32_e32 v66, s49
	v_cndmask_b32_e32 v66, v66, v68, vcc
	v_lshl_add_u64 v[68:69], v[64:65], 0, v[140:141]
	v_add_co_u32_e32 v64, vcc, 0x80000, v68
	v_lshl_add_u64 v[66:67], v[66:67], 0, v[140:141]
	s_nop 0
	v_addc_co_u32_e32 v65, vcc, 0, v69, vcc
	global_load_dwordx4 v[214:217], v[66:67], off
	global_load_dwordx4 v[218:221], v[66:67], off offset:64
	global_load_dwordx4 v[222:225], v[66:67], off offset:512
	global_load_dwordx4 v[226:229], v[66:67], off offset:576
	global_load_dwordx4 v[230:233], v[64:65], off
	global_load_dwordx4 v[234:237], v[64:65], off offset:64
	global_load_dwordx4 v[238:241], v[64:65], off offset:512
	global_load_dwordx4 v[242:245], v[64:65], off offset:576
	v_add_u32_e32 v64, 0xffffff80, v138
	s_movk_i32 s10, 0x7f
	v_mov_b32_e32 v65, v144
	v_cmp_lt_i32_e64 s[10:11], s10, v138
	v_lshlrev_b64 v[64:65], 12, v[64:65]
	s_and_b64 vcc, exec, s[8:9]
	s_waitcnt vmcnt(3)
	v_pk_fma_f32 v[62:63], v[62:63], v[216:217], v[232:233]
	v_pk_fma_f32 v[60:61], v[60:61], v[214:215], v[230:231]
	s_cbranch_vccnz .LBB0_3035
	s_and_saveexec_b64 s[24:25], s[10:11]
	s_cbranch_execz .LBB0_2943
	v_lshl_add_u64 v[70:71], s[16:17], 0, v[64:65]
	v_lshl_add_u64 v[70:71], v[136:137], 2, v[70:71]
	global_store_dwordx4 v[70:71], v[60:63], off

.LBB0_2945:
	s_nop 0
	s_and_b64 vcc, exec, s[8:9]
	s_waitcnt vmcnt(3)
	v_pk_fma_f32 v[58:59], v[58:59], v[220:221], v[236:237]
	v_pk_fma_f32 v[56:57], v[56:57], v[218:219], v[234:235]
	s_cbranch_vccnz .LBB0_3036
	s_and_saveexec_b64 s[24:25], s[10:11]
	s_cbranch_execz .LBB0_2948
	v_lshl_add_u64 v[60:61], s[16:17], 0, v[64:65]
	v_lshl_add_u64 v[60:61], v[136:137], 2, v[60:61]
	global_store_dwordx4 v[60:61], v[56:59], off offset:64

.LBB0_2950:
	s_nop 0
	s_and_b64 vcc, exec, s[8:9]
	s_waitcnt vmcnt(3)
	v_pk_fma_f32 v[54:55], v[54:55], v[224:225], v[240:241]
	v_pk_fma_f32 v[52:53], v[52:53], v[222:223], v[238:239]
	s_cbranch_vccnz .LBB0_3037
	s_and_saveexec_b64 s[24:25], s[10:11]
	s_cbranch_execz .LBB0_2953
	v_lshl_add_u64 v[56:57], s[16:17], 0, v[64:65]
	v_lshl_add_u64 v[56:57], v[136:137], 2, v[56:57]
	global_store_dwordx4 v[56:57], v[52:55], off offset:512

.LBB0_2955:
	s_nop 0
	s_and_b64 vcc, exec, s[8:9]
	s_waitcnt vmcnt(3)
	v_pk_fma_f32 v[50:51], v[50:51], v[228:229], v[244:245]
	v_pk_fma_f32 v[48:49], v[48:49], v[226:227], v[242:243]
	s_cbranch_vccnz .LBB0_3038
	s_and_saveexec_b64 s[24:25], s[10:11]
	s_cbranch_execz .LBB0_2958
	v_lshl_add_u64 v[52:53], s[16:17], 0, v[64:65]
	v_lshl_add_u64 v[52:53], v[136:137], 2, v[52:53]
	global_store_dwordx4 v[52:53], v[48:51], off offset:576

.LBB0_2960:
	s_nop 1
	v_lshlrev_b64 v[48:49], 12, v[138:139]
	v_mov_b32_e32 v50, s51
	v_mov_b32_e32 v51, s59
	v_cmp_gt_i32_e32 vcc, s40, v138
	v_mov_b32_e32 v52, s58
	v_lshl_add_u64 v[48:49], s[14:15], 0, v[48:49]
	v_cndmask_b32_e32 v51, v50, v51, vcc
	v_mov_b32_e32 v50, s49
	v_cndmask_b32_e32 v50, v50, v52, vcc
	v_lshl_add_u64 v[52:53], v[48:49], 0, v[140:141]
	v_add_co_u32_e32 v48, vcc, 0x90000, v52
	v_lshl_add_u64 v[50:51], v[50:51], 0, v[140:141]
	s_nop 0
	v_addc_co_u32_e32 v49, vcc, 0, v53, vcc
	global_load_dwordx4 v[214:217], v[50:51], off
	global_load_dwordx4 v[218:221], v[50:51], off offset:64
	global_load_dwordx4 v[222:225], v[50:51], off offset:512
	global_load_dwordx4 v[226:229], v[50:51], off offset:576
	global_load_dwordx4 v[230:233], v[48:49], off
	global_load_dwordx4 v[234:237], v[48:49], off offset:64
	global_load_dwordx4 v[238:241], v[48:49], off offset:512
	global_load_dwordx4 v[242:245], v[48:49], off offset:576
	v_add_u32_e32 v48, 0xffffff90, v138
	s_movk_i32 s10, 0x6f
	v_mov_b32_e32 v49, v144
	v_cmp_lt_i32_e64 s[10:11], s10, v138
	v_lshlrev_b64 v[48:49], 12, v[48:49]
	s_and_b64 vcc, exec, s[8:9]
	s_waitcnt vmcnt(3)
	v_pk_fma_f32 v[46:47], v[46:47], v[216:217], v[232:233]
	v_pk_fma_f32 v[44:45], v[44:45], v[214:215], v[230:231]
	s_cbranch_vccnz .LBB0_3039
	s_and_saveexec_b64 s[24:25], s[10:11]
	s_cbranch_execz .LBB0_2963
	v_lshl_add_u64 v[54:55], s[16:17], 0, v[48:49]
	v_lshl_add_u64 v[54:55], v[136:137], 2, v[54:55]
	global_store_dwordx4 v[54:55], v[44:47], off

.LBB0_2965:
	s_nop 0
	s_and_b64 vcc, exec, s[8:9]
	s_waitcnt vmcnt(3)
	v_pk_fma_f32 v[42:43], v[42:43], v[220:221], v[236:237]
	v_pk_fma_f32 v[40:41], v[40:41], v[218:219], v[234:235]
	s_cbranch_vccnz .LBB0_3040
	s_and_saveexec_b64 s[24:25], s[10:11]
	s_cbranch_execz .LBB0_2968
	v_lshl_add_u64 v[44:45], s[16:17], 0, v[48:49]
	v_lshl_add_u64 v[44:45], v[136:137], 2, v[44:45]
	global_store_dwordx4 v[44:45], v[40:43], off offset:64

.LBB0_2970:
	s_nop 0
	s_and_b64 vcc, exec, s[8:9]
	s_waitcnt vmcnt(3)
	v_pk_fma_f32 v[38:39], v[38:39], v[224:225], v[240:241]
	v_pk_fma_f32 v[36:37], v[36:37], v[222:223], v[238:239]
	s_cbranch_vccnz .LBB0_3041
	s_and_saveexec_b64 s[24:25], s[10:11]
	s_cbranch_execz .LBB0_2973
	v_lshl_add_u64 v[40:41], s[16:17], 0, v[48:49]
	v_lshl_add_u64 v[40:41], v[136:137], 2, v[40:41]
	global_store_dwordx4 v[40:41], v[36:39], off offset:512

.LBB0_2975:
	s_nop 0
	s_and_b64 vcc, exec, s[8:9]
	s_waitcnt vmcnt(3)
	v_pk_fma_f32 v[34:35], v[34:35], v[228:229], v[244:245]
	v_pk_fma_f32 v[32:33], v[32:33], v[226:227], v[242:243]
	s_cbranch_vccnz .LBB0_3042
	s_and_saveexec_b64 s[24:25], s[10:11]
	s_cbranch_execz .LBB0_2978
	v_lshl_add_u64 v[36:37], s[16:17], 0, v[48:49]
	v_lshl_add_u64 v[36:37], v[136:137], 2, v[36:37]
	global_store_dwordx4 v[36:37], v[32:35], off offset:576

.LBB0_2980:
	s_nop 1
	v_lshlrev_b64 v[32:33], 12, v[138:139]
	v_mov_b32_e32 v34, s51
	v_mov_b32_e32 v35, s59
	v_cmp_gt_i32_e32 vcc, s91, v138
	v_mov_b32_e32 v36, s58
	v_lshl_add_u64 v[32:33], s[14:15], 0, v[32:33]
	v_cndmask_b32_e32 v35, v34, v35, vcc
	v_mov_b32_e32 v34, s49
	v_cndmask_b32_e32 v34, v34, v36, vcc
	v_lshl_add_u64 v[36:37], v[32:33], 0, v[140:141]
	v_add_co_u32_e32 v32, vcc, 0xa0000, v36
	v_lshl_add_u64 v[34:35], v[34:35], 0, v[140:141]
	s_nop 0
	v_addc_co_u32_e32 v33, vcc, 0, v37, vcc
	global_load_dwordx4 v[214:217], v[34:35], off
	global_load_dwordx4 v[218:221], v[34:35], off offset:64
	global_load_dwordx4 v[222:225], v[34:35], off offset:512
	global_load_dwordx4 v[226:229], v[34:35], off offset:576
	global_load_dwordx4 v[230:233], v[32:33], off
	global_load_dwordx4 v[234:237], v[32:33], off offset:64
	global_load_dwordx4 v[238:241], v[32:33], off offset:512
	global_load_dwordx4 v[242:245], v[32:33], off offset:576
	v_add_u32_e32 v32, 0xffffffa0, v138
	s_movk_i32 s10, 0x5f
	v_mov_b32_e32 v33, v144
	v_cmp_lt_i32_e64 s[10:11], s10, v138
	v_lshlrev_b64 v[32:33], 12, v[32:33]
	s_and_b64 vcc, exec, s[8:9]
	s_waitcnt vmcnt(3)
	v_pk_fma_f32 v[30:31], v[30:31], v[216:217], v[232:233]
	v_pk_fma_f32 v[28:29], v[28:29], v[214:215], v[230:231]
	s_cbranch_vccnz .LBB0_3043
	s_and_saveexec_b64 s[24:25], s[10:11]
	s_cbranch_execz .LBB0_2983
	v_lshl_add_u64 v[38:39], s[16:17], 0, v[32:33]
	v_lshl_add_u64 v[38:39], v[136:137], 2, v[38:39]
	global_store_dwordx4 v[38:39], v[28:31], off

.LBB0_2985:
	s_nop 0
	s_and_b64 vcc, exec, s[8:9]
	s_waitcnt vmcnt(3)
	v_pk_fma_f32 v[26:27], v[26:27], v[220:221], v[236:237]
	v_pk_fma_f32 v[24:25], v[24:25], v[218:219], v[234:235]
	s_cbranch_vccnz .LBB0_3044
	s_and_saveexec_b64 s[24:25], s[10:11]
	s_cbranch_execz .LBB0_2988
	v_lshl_add_u64 v[28:29], s[16:17], 0, v[32:33]
	v_lshl_add_u64 v[28:29], v[136:137], 2, v[28:29]
	global_store_dwordx4 v[28:29], v[24:27], off offset:64

.LBB0_2990:
	s_nop 0
	s_and_b64 vcc, exec, s[8:9]
	s_waitcnt vmcnt(3)
	v_pk_fma_f32 v[22:23], v[22:23], v[224:225], v[240:241]
	v_pk_fma_f32 v[20:21], v[20:21], v[222:223], v[238:239]
	s_cbranch_vccnz .LBB0_3045
	s_and_saveexec_b64 s[24:25], s[10:11]
	s_cbranch_execz .LBB0_2993
	v_lshl_add_u64 v[24:25], s[16:17], 0, v[32:33]
	v_lshl_add_u64 v[24:25], v[136:137], 2, v[24:25]
	global_store_dwordx4 v[24:25], v[20:23], off offset:512

.LBB0_2995:
	s_nop 0
	s_and_b64 vcc, exec, s[8:9]
	s_waitcnt vmcnt(3)
	v_pk_fma_f32 v[18:19], v[18:19], v[228:229], v[244:245]
	v_pk_fma_f32 v[16:17], v[16:17], v[226:227], v[242:243]
	s_cbranch_vccnz .LBB0_3046
	s_and_saveexec_b64 s[24:25], s[10:11]
	s_cbranch_execz .LBB0_2998
	v_lshl_add_u64 v[20:21], s[16:17], 0, v[32:33]
	v_lshl_add_u64 v[20:21], v[136:137], 2, v[20:21]
	global_store_dwordx4 v[20:21], v[16:19], off offset:576

.LBB0_3000:
	s_nop 1
	v_lshlrev_b64 v[16:17], 12, v[138:139]
	v_mov_b32_e32 v18, s51
	v_mov_b32_e32 v19, s59
	v_cmp_gt_i32_e32 vcc, s41, v138
	v_mov_b32_e32 v20, s58
	v_lshl_add_u64 v[16:17], s[14:15], 0, v[16:17]
	v_cndmask_b32_e32 v19, v18, v19, vcc
	v_mov_b32_e32 v18, s49
	v_cndmask_b32_e32 v18, v18, v20, vcc
	v_lshl_add_u64 v[20:21], v[16:17], 0, v[140:141]
	v_add_co_u32_e32 v16, vcc, 0xb0000, v20
	v_lshl_add_u64 v[18:19], v[18:19], 0, v[140:141]
	s_nop 0
	v_addc_co_u32_e32 v17, vcc, 0, v21, vcc
	global_load_dwordx4 v[214:217], v[18:19], off
	global_load_dwordx4 v[218:221], v[18:19], off offset:64
	global_load_dwordx4 v[222:225], v[18:19], off offset:512
	global_load_dwordx4 v[226:229], v[18:19], off offset:576
	global_load_dwordx4 v[230:233], v[16:17], off
	global_load_dwordx4 v[234:237], v[16:17], off offset:64
	global_load_dwordx4 v[238:241], v[16:17], off offset:512
	global_load_dwordx4 v[242:245], v[16:17], off offset:576
	v_add_u32_e32 v16, 0xffffffb0, v138
	s_movk_i32 s10, 0x4f
	v_mov_b32_e32 v17, v144
	v_cmp_lt_i32_e64 s[10:11], s10, v138
	v_lshlrev_b64 v[16:17], 12, v[16:17]
	s_and_b64 vcc, exec, s[8:9]
	s_waitcnt vmcnt(3)
	v_pk_fma_f32 v[14:15], v[14:15], v[216:217], v[232:233]
	v_pk_fma_f32 v[12:13], v[12:13], v[214:215], v[230:231]
	s_cbranch_vccnz .LBB0_3047
	s_and_saveexec_b64 s[24:25], s[10:11]
	s_cbranch_execz .LBB0_3003
	v_lshl_add_u64 v[22:23], s[16:17], 0, v[16:17]
	v_lshl_add_u64 v[22:23], v[136:137], 2, v[22:23]
	global_store_dwordx4 v[22:23], v[12:15], off

.LBB0_3005:
	s_nop 0
	s_and_b64 vcc, exec, s[8:9]
	s_waitcnt vmcnt(3)
	v_pk_fma_f32 v[10:11], v[10:11], v[220:221], v[236:237]
	v_pk_fma_f32 v[8:9], v[8:9], v[218:219], v[234:235]
	s_cbranch_vccnz .LBB0_3048
	s_and_saveexec_b64 s[24:25], s[10:11]
	s_cbranch_execz .LBB0_3008
	v_lshl_add_u64 v[12:13], s[16:17], 0, v[16:17]
	v_lshl_add_u64 v[12:13], v[136:137], 2, v[12:13]
	global_store_dwordx4 v[12:13], v[8:11], off offset:64

.LBB0_3010:
	s_nop 0
	s_and_b64 vcc, exec, s[8:9]
	s_waitcnt vmcnt(3)
	v_pk_fma_f32 v[6:7], v[6:7], v[224:225], v[240:241]
	v_pk_fma_f32 v[4:5], v[4:5], v[222:223], v[238:239]
	s_cbranch_vccnz .LBB0_3049
	s_and_saveexec_b64 s[24:25], s[10:11]
	s_cbranch_execz .LBB0_3013
	v_lshl_add_u64 v[8:9], s[16:17], 0, v[16:17]
	v_lshl_add_u64 v[8:9], v[136:137], 2, v[8:9]
	global_store_dwordx4 v[8:9], v[4:7], off offset:512

.LBB0_3015:
	s_nop 0
	s_and_b64 vcc, exec, s[8:9]
	s_waitcnt vmcnt(3)
	v_pk_fma_f32 v[2:3], v[2:3], v[228:229], v[244:245]
	v_pk_fma_f32 v[0:1], v[0:1], v[226:227], v[242:243]
	s_cbranch_vccnz .LBB0_3050
	s_and_saveexec_b64 s[8:9], s[10:11]
	s_cbranch_execz .LBB0_3018
	v_lshl_add_u64 v[4:5], s[16:17], 0, v[16:17]
	v_lshl_add_u64 v[4:5], v[136:137], 2, v[4:5]
	global_store_dwordx4 v[4:5], v[0:3], off offset:576
